# v19 plus: first V-fragment LDS reads fill the post-QK MFMA hazard slots; diff loops: next-iteration parity, LDS base and read addresses computed before the tile barrier (back-edge rotation)
# speedup vs baseline: 1.0214x; 1.0020x over previous
; #define LAS __attribute__((address_space(3)))
; template <bool DIFF> ...
;     ...
;     for (int t = 0; t < NT; ++t) {
;         const int buf = t & 1;
;         if (t + 1 < NT) ATT_GLOAD(t + 1);
;         if (t < nt_w) {
;             const LAS unsigned char* kb_ = lds + buf * BUFB; const LAS unsigned char* vb_ = kb_ + KTILEB;
;             f32x16 pr[2];
;             const LAS unsigned char* vbase = vb_ + (4 * hi + ((lane & 15) >> 2)) * VROWB + (sdv + ((lane >> 4) & 1) * 16 + (lane & 3) * 4) * 2;
;     ...
;             bf16x8 vfa[NDB], vfb[NDB];
;             {
;                 bf16x8 kf[2][NS];
; #pragma unroll
;                 for (int kb = 0; kb < 2; ++kb)
; #pragma unroll
;                     for (int st = 0; st < NS; ++st) kf[kb][st] = *(const LAS bf16x8*)(kb_ + (kb * 32 + l32) * KROWB + (s * DQK + st * 16 + hi * 8) * 2);
;                 VLOAD(vfa, 0);
;                 __builtin_amdgcn_sched_barrier(0);
;                 __builtin_amdgcn_s_setprio(1);
; #pragma unroll
;                 for (int st = 0; st < NS; ++st) {
;                     pr[0] = __builtin_amdgcn_mfma_f32_32x32x16_bf16(kf[0][st], qf[st], st == 0 ? negm : pr[0], 0, 0, 0);
;                     pr[1] = __builtin_amdgcn_mfma_f32_32x32x16_bf16(kf[1][st], qf[st], st == 0 ? negm : pr[1], 0, 0, 0); }
;                 __builtin_amdgcn_s_setprio(0);
;             }
;             const int tp0 = (t == 0) ? -16 : (t - 1) * 64;
;             if (DIFF) {
;                 if (tp0 + 63 - qpos_w > -128) {
; #pragma unroll
;                     for (int kb = 0; kb < 2; ++kb)
; #pragma unroll
;                         for (int r = 0; r < 16; ++r) { const int kvi = kb * 32 + 8 * (r >> 2) + 4 * hi + (r & 3); int idx = tp0 + kvi - qpos + 128; idx = idx < 0 ? 0 : idx; pr[kb][r] += lut[idx]; }
;                 }
;             }
.Lbody_d1:
	ds_read_b128 v[80:83], v97
	ds_read_b128 v[84:87], v97 offset:32
	ds_read_b128 v[88:91], v97 offset:64
	ds_read_b128 v[92:95], v97 offset:96
	ds_read_b128 v[222:225], v97 offset:8704
	ds_read_b128 v[226:229], v97 offset:8736
	ds_read_b128 v[230:233], v97 offset:8768
	ds_read_b128 v[234:237], v97 offset:8800
	ds_read_b64_tr_b16 v[174:175], v221 offset:17408
	ds_read_b64_tr_b16 v[170:171], v221 offset:17472
	ds_read_b64_tr_b16 v[166:167], v221 offset:17536
	ds_read_b64_tr_b16 v[162:163], v221 offset:17600
	ds_read_b64_tr_b16 v[176:177], v221 offset:19968
	ds_read_b64_tr_b16 v[172:173], v221 offset:20032
	ds_read_b64_tr_b16 v[168:169], v221 offset:20096
	ds_read_b64_tr_b16 v[164:165], v221 offset:20160
	s_setprio 1
	s_waitcnt lgkmcnt(14)
	v_mfma_f32_32x32x16_bf16 v[112:127], v[80:83], v[142:145], v[64:79]
	s_waitcnt lgkmcnt(11)
	v_mfma_f32_32x32x16_bf16 v[96:111], v[222:225], v[142:145], v[64:79]
	v_add_u32_e32 v80, s47, v220
	v_ashrrev_i32_e32 v81, 31, v80
	v_add_u32_e32 v82, s47, v219
	v_lshlrev_b64 v[80:81], 11, v[80:81]
	v_mfma_f32_32x32x16_bf16 v[112:127], v[84:87], v[138:141], v[112:127]
	v_ashrrev_i32_e32 v83, 31, v82
	v_lshl_add_u64 v[80:81], v[190:191], 0, v[80:81]
	v_lshlrev_b64 v[82:83], 11, v[82:83]
	v_lshl_add_u64 v[82:83], v[192:193], 0, v[82:83]
	global_load_dwordx4 v[146:149], v[80:81], off
	global_load_dwordx4 v[150:153], v[82:83], off
	s_waitcnt lgkmcnt(10)
	v_mfma_f32_32x32x16_bf16 v[96:111], v[226:229], v[138:141], v[96:111]
	v_add_u32_e32 v80, s47, v218
	v_ashrrev_i32_e32 v81, 31, v80
	v_add_u32_e32 v82, s47, v217
	v_lshlrev_b64 v[80:81], 11, v[80:81]
	v_mfma_f32_32x32x16_bf16 v[112:127], v[88:91], v[134:137], v[112:127]
	v_ashrrev_i32_e32 v83, 31, v82
	v_lshl_add_u64 v[80:81], v[188:189], 0, v[80:81]
	v_lshlrev_b64 v[82:83], 11, v[82:83]
	v_lshl_add_u64 v[82:83], v[188:189], 0, v[82:83]
	global_load_dwordx4 v[154:157], v[80:81], off
	global_load_dwordx4 v[158:161], v[82:83], off
	s_waitcnt lgkmcnt(9)
	v_mfma_f32_32x32x16_bf16 v[96:111], v[230:233], v[134:137], v[96:111]
	v_mfma_f32_32x32x16_bf16 v[112:127], v[92:95], v[130:133], v[112:127]
	s_waitcnt lgkmcnt(8)
	v_mfma_f32_32x32x16_bf16 v[96:111], v[234:237], v[130:133], v[96:111]
	s_setprio 0
	s_add_i32 s46, s47, 64
	s_cmp_le_i32 s46, s44
	s_cbranch_scc1 .LBB0_340
	v_add_u32_e32 v200, s47, v216
	s_add_i32 s1, 0, 0x18000
	v_max_i32_e32 v222, 0xffffff5d, v200
	v_lshl_add_u32 v223, v222, 2, s1
	v_max_i32_e32 v222, 0xffffff58, v200
	v_max_i32_e32 v228, 0xffffff4f, v200
	v_lshl_add_u32 v224, v222, 2, s1
	v_max_i32_e32 v222, 0xffffff57, v200
	v_lshl_add_u32 v229, v228, 2, s1
	v_max_i32_e32 v228, 0xffffff4e, v200
	v_lshl_add_u32 v225, v222, 2, s1
	v_max_i32_e32 v222, 0xffffff56, v200
	v_lshl_add_u32 v230, v228, 2, s1
	v_max_i32_e32 v228, 0xffffff4d, v200
	v_max_i32_e32 v80, 0xffffff80, v200
	v_max_i32_e32 v81, 0xffffff7f, v200
	v_max_i32_e32 v82, 0xffffff7e, v200
	v_max_i32_e32 v83, 0xffffff7d, v200
	v_max_i32_e32 v84, 0xffffff78, v200
	v_max_i32_e32 v85, 0xffffff77, v200
	v_max_i32_e32 v86, 0xffffff76, v200
	v_max_i32_e32 v87, 0xffffff75, v200
	v_max_i32_e32 v88, 0xffffff70, v200
	v_max_i32_e32 v89, 0xffffff6f, v200
	v_max_i32_e32 v90, 0xffffff6e, v200
	v_max_i32_e32 v91, 0xffffff6d, v200
	v_max_i32_e32 v92, 0xffffff68, v200
	v_max_i32_e32 v93, 0xffffff67, v200
	v_max_i32_e32 v94, 0xffffff66, v200
	v_max_i32_e32 v95, 0xffffff65, v200
	v_max_i32_e32 v198, 0xffffff60, v200
	v_max_i32_e32 v199, 0xffffff5f, v200
	v_max_i32_e32 v201, 0xffffff5e, v200
	v_lshl_add_u32 v226, v222, 2, s1
	v_max_i32_e32 v222, 0xffffff55, v200
	v_lshl_add_u32 v231, v228, 2, s1
	v_max_i32_e32 v228, 0xffffff48, v200
	v_lshl_add_u32 v80, v80, 2, s1
	v_lshl_add_u32 v81, v81, 2, s1
	v_lshl_add_u32 v82, v82, 2, s1
	v_lshl_add_u32 v83, v83, 2, s1
	v_lshl_add_u32 v84, v84, 2, s1
	v_lshl_add_u32 v85, v85, 2, s1
	v_lshl_add_u32 v86, v86, 2, s1
	v_lshl_add_u32 v87, v87, 2, s1
	v_lshl_add_u32 v88, v88, 2, s1
	v_lshl_add_u32 v89, v89, 2, s1
	v_lshl_add_u32 v90, v90, 2, s1
	v_lshl_add_u32 v91, v91, 2, s1
	v_lshl_add_u32 v92, v92, 2, s1
	v_lshl_add_u32 v93, v93, 2, s1
	v_lshl_add_u32 v94, v94, 2, s1
	v_lshl_add_u32 v95, v95, 2, s1
	v_lshl_add_u32 v198, v198, 2, s1
	v_lshl_add_u32 v199, v199, 2, s1
	v_lshl_add_u32 v201, v201, 2, s1
	v_lshl_add_u32 v227, v222, 2, s1
	v_lshl_add_u32 v232, v228, 2, s1
	v_max_i32_e32 v228, 0xffffff47, v200
	ds_read_b32 v80, v80 offset:512
	ds_read_b32 v81, v81 offset:516
	ds_read_b32 v82, v82 offset:520
	ds_read_b32 v83, v83 offset:524
	ds_read_b32 v84, v84 offset:544
	ds_read_b32 v85, v85 offset:548
	ds_read_b32 v86, v86 offset:552
	ds_read_b32 v87, v87 offset:556
	ds_read_b32 v88, v88 offset:576
	ds_read_b32 v89, v89 offset:580
	ds_read_b32 v90, v90 offset:584
	ds_read_b32 v91, v91 offset:588
	ds_read_b32 v92, v92 offset:608
	ds_read_b32 v93, v93 offset:612
	ds_read_b32 v94, v94 offset:616
	ds_read_b32 v95, v95 offset:620
	ds_read_b32 v198, v198 offset:640
	ds_read_b32 v199, v199 offset:644
	ds_read_b32 v222, v201 offset:648
	ds_read_b32 v223, v223 offset:652
	ds_read_b32 v224, v224 offset:672
	ds_read_b32 v225, v225 offset:676
	ds_read_b32 v226, v226 offset:680
	ds_read_b32 v227, v227 offset:684
	v_max_i32_e32 v201, 0xffffff50, v200
	v_lshl_add_u32 v233, v228, 2, s1
	v_max_i32_e32 v228, 0xffffff46, v200
	v_lshl_add_u32 v201, v201, 2, s1
	v_lshl_add_u32 v234, v228, 2, s1
	v_max_i32_e32 v200, 0xffffff45, v200
	v_lshl_add_u32 v200, v200, 2, s1
	ds_read_b32 v228, v201 offset:704
	ds_read_b32 v229, v229 offset:708
	ds_read_b32 v230, v230 offset:712
	ds_read_b32 v231, v231 offset:716
	ds_read_b32 v232, v232 offset:736
	ds_read_b32 v233, v233 offset:740
	ds_read_b32 v234, v234 offset:744
	ds_read_b32 v235, v200 offset:748
	s_waitcnt lgkmcnt(14)
	v_pk_add_f32 v[126:127], v[126:127], v[94:95]
	v_pk_add_f32 v[124:125], v[124:125], v[92:93]
	v_pk_add_f32 v[122:123], v[122:123], v[90:91]
	v_pk_add_f32 v[120:121], v[120:121], v[88:89]
	v_pk_add_f32 v[118:119], v[118:119], v[86:87]
	v_pk_add_f32 v[116:117], v[116:117], v[84:85]
	v_pk_add_f32 v[114:115], v[114:115], v[82:83]
	v_pk_add_f32 v[112:113], v[112:113], v[80:81]
	s_waitcnt lgkmcnt(0)
	v_pk_add_f32 v[110:111], v[110:111], v[234:235]
	v_pk_add_f32 v[108:109], v[108:109], v[232:233]
	v_pk_add_f32 v[106:107], v[106:107], v[230:231]
	v_pk_add_f32 v[104:105], v[104:105], v[228:229]
	v_pk_add_f32 v[102:103], v[102:103], v[226:227]
	v_pk_add_f32 v[100:101], v[100:101], v[224:225]
	v_pk_add_f32 v[98:99], v[98:99], v[222:223]
	v_pk_add_f32 v[96:97], v[96:97], v[198:199]
; __device__ __forceinline__ float shx(float v, int mask, int lane) { return __int_as_float(__builtin_amdgcn_ds_bpermute((lane ^ mask) << 2, __float_as_int(v))); }
; template <bool DIFF> ...
;     ...
;             float mx;
;             { float a0 = fmaxf(fmaxf(pr[0][0], pr[0][1]), pr[0][2]), a1 = fmaxf(fmaxf(pr[1][0], pr[1][1]), pr[1][2]);
; #pragma unroll
;               for (int r = 3; r < 15; r += 2) { a0 = fmaxf(fmaxf(a0, pr[0][r]), pr[0][r + 1]); a1 = fmaxf(fmaxf(a1, pr[1][r]), pr[1][r + 1]); }
;               mx = fmaxf(fmaxf(a0, a1), fmaxf(pr[0][15], pr[1][15])); }
;             mx = fmaxf(mx, shx(mx, 32, lane));
;             if (t == 0 || __any(mx > 8.0f)) {
;                 const float dl = (t == 0) ? mx : fmaxf(mx, 0.f);
;                 mrun += dl;
; #pragma unroll
;                 for (int r = 0; r < 16; ++r) negm[r] = -mrun;
;                 const float alpha = (t == 0) ? 1.f : __builtin_amdgcn_exp2f(-dl); lsum *= alpha;
; #pragma unroll
;                 for (int kb = 0; kb < 2; ++kb) pr[kb] = pr[kb] - dl;
; #pragma unroll
;                 for (int db = 0; db < NDB; ++db) o[db] = o[db] * alpha;
;             }
.LBB0_340:
	ds_read_b64_tr_b16 v[224:225], v221 offset:22528
	ds_read_b64_tr_b16 v[228:229], v221 offset:22592
	ds_read_b64_tr_b16 v[232:233], v221 offset:22656
	ds_read_b64_tr_b16 v[92:93], v221 offset:22720
	ds_read_b64_tr_b16 v[226:227], v221 offset:25088
	ds_read_b64_tr_b16 v[230:231], v221 offset:25152
	ds_read_b64_tr_b16 v[234:235], v221 offset:25216
	ds_read_b64_tr_b16 v[94:95], v221 offset:25280
	v_max3_f32 v80, v112, v113, v114
	s_nop 0
	v_max3_f32 v81, v96, v97, v98
	v_max3_f32 v80, v80, v115, v116
	v_max3_f32 v81, v81, v99, v100
	v_max3_f32 v80, v80, v117, v118
	v_max3_f32 v81, v81, v101, v102
	v_max3_f32 v80, v80, v119, v120
	v_max3_f32 v81, v81, v103, v104
	v_max3_f32 v80, v80, v121, v122
	v_max3_f32 v81, v81, v105, v106
	v_max3_f32 v80, v80, v123, v124
	v_max3_f32 v81, v81, v107, v108
	v_max_f32_e32 v82, v111, v111
	v_max_f32_e32 v83, v127, v127
	v_max3_f32 v80, v80, v125, v126
	v_max3_f32 v81, v81, v109, v110
	v_max_f32_e32 v82, v83, v82
	v_max3_f32 v80, v80, v81, v82
	v_cmp_lt_f32_e32 vcc, s33, v80
	s_cbranch_vccz .LBB0_343
	ds_bpermute_b32 v81, v204, v80
	s_waitcnt lgkmcnt(0)
	v_max_f32_e32 v81, v81, v81
	v_max_f32_e32 v80, v80, v81
	v_max_f32_e32 v64, v80, v80
	v_max_f32_e32 v65, 0, v64
	v_exp_f32_e64 v66, -v65
	v_add_f32_e32 v186, v186, v65
	v_xor_b32_e32 v64, 0x80000000, v186
	v_sub_f32_e32 v112, v112, v65
	v_sub_f32_e32 v113, v113, v65
	v_sub_f32_e32 v114, v114, v65
	v_sub_f32_e32 v127, v127, v65
	v_sub_f32_e32 v115, v115, v65
	v_sub_f32_e32 v116, v116, v65
	v_sub_f32_e32 v117, v117, v65
	v_sub_f32_e32 v118, v118, v65
	v_sub_f32_e32 v119, v119, v65
	v_sub_f32_e32 v120, v120, v65
	v_sub_f32_e32 v121, v121, v65
	v_sub_f32_e32 v122, v122, v65
	v_sub_f32_e32 v123, v123, v65
	v_sub_f32_e32 v124, v124, v65
	v_sub_f32_e32 v125, v125, v65
	v_sub_f32_e32 v126, v126, v65
	v_sub_f32_e32 v96, v96, v65
	v_sub_f32_e32 v97, v97, v65
	v_sub_f32_e32 v98, v98, v65
	v_sub_f32_e32 v99, v99, v65
	v_sub_f32_e32 v100, v100, v65
	v_sub_f32_e32 v101, v101, v65
	v_sub_f32_e32 v102, v102, v65
	v_sub_f32_e32 v103, v103, v65
	v_sub_f32_e32 v104, v104, v65
	v_sub_f32_e32 v105, v105, v65
	v_sub_f32_e32 v106, v106, v65
	v_sub_f32_e32 v107, v107, v65
	v_sub_f32_e32 v108, v108, v65
	v_sub_f32_e32 v109, v109, v65
	v_sub_f32_e32 v110, v110, v65
	v_sub_f32_e32 v111, v111, v65
	v_pk_mul_f32 v[62:63], v[62:63], v[66:67] op_sel_hi:[1,0]
	v_pk_mul_f32 v[60:61], v[60:61], v[66:67] op_sel_hi:[1,0]
	v_pk_mul_f32 v[58:59], v[58:59], v[66:67] op_sel_hi:[1,0]
	v_pk_mul_f32 v[56:57], v[56:57], v[66:67] op_sel_hi:[1,0]
	v_pk_mul_f32 v[54:55], v[54:55], v[66:67] op_sel_hi:[1,0]
	v_pk_mul_f32 v[52:53], v[52:53], v[66:67] op_sel_hi:[1,0]
	v_pk_mul_f32 v[50:51], v[50:51], v[66:67] op_sel_hi:[1,0]
	v_pk_mul_f32 v[48:49], v[48:49], v[66:67] op_sel_hi:[1,0]
	v_pk_mul_f32 v[46:47], v[46:47], v[66:67] op_sel_hi:[1,0]
	v_pk_mul_f32 v[44:45], v[44:45], v[66:67] op_sel_hi:[1,0]
	v_pk_mul_f32 v[42:43], v[42:43], v[66:67] op_sel_hi:[1,0]
	v_pk_mul_f32 v[40:41], v[40:41], v[66:67] op_sel_hi:[1,0]
	v_pk_mul_f32 v[38:39], v[38:39], v[66:67] op_sel_hi:[1,0]
	v_pk_mul_f32 v[36:37], v[36:37], v[66:67] op_sel_hi:[1,0]
	v_pk_mul_f32 v[34:35], v[34:35], v[66:67] op_sel_hi:[1,0]
	v_pk_mul_f32 v[32:33], v[32:33], v[66:67] op_sel_hi:[1,0]
	v_pk_mul_f32 v[30:31], v[30:31], v[66:67] op_sel_hi:[1,0]
	v_pk_mul_f32 v[28:29], v[28:29], v[66:67] op_sel_hi:[1,0]
	v_pk_mul_f32 v[26:27], v[26:27], v[66:67] op_sel_hi:[1,0]
	v_pk_mul_f32 v[24:25], v[24:25], v[66:67] op_sel_hi:[1,0]
	v_pk_mul_f32 v[22:23], v[22:23], v[66:67] op_sel_hi:[1,0]
	v_pk_mul_f32 v[20:21], v[20:21], v[66:67] op_sel_hi:[1,0]
	v_pk_mul_f32 v[18:19], v[18:19], v[66:67] op_sel_hi:[1,0]
	v_pk_mul_f32 v[16:17], v[16:17], v[66:67] op_sel_hi:[1,0]
	v_pk_mul_f32 v[14:15], v[14:15], v[66:67] op_sel_hi:[1,0]
	v_pk_mul_f32 v[12:13], v[12:13], v[66:67] op_sel_hi:[1,0]
	v_pk_mul_f32 v[10:11], v[10:11], v[66:67] op_sel_hi:[1,0]
	v_pk_mul_f32 v[8:9], v[8:9], v[66:67] op_sel_hi:[1,0]
	v_pk_mul_f32 v[6:7], v[6:7], v[66:67] op_sel_hi:[1,0]
	v_pk_mul_f32 v[4:5], v[4:5], v[66:67] op_sel_hi:[1,0]
	v_pk_mul_f32 v[2:3], v[2:3], v[66:67] op_sel_hi:[1,0]
	v_pk_mul_f32 v[0:1], v[0:1], v[66:67] op_sel_hi:[1,0]
	v_mul_f32_e32 v187, v187, v66
	v_mov_b32_e32 v65, v64
	v_mov_b32_e32 v66, v64
	v_mov_b32_e32 v67, v64
	v_mov_b32_e32 v68, v64
	v_mov_b32_e32 v69, v64
	v_mov_b32_e32 v70, v64
	v_mov_b32_e32 v71, v64
	v_mov_b32_e32 v72, v64
	v_mov_b32_e32 v73, v64
	v_mov_b32_e32 v74, v64
	v_mov_b32_e32 v75, v64
	v_mov_b32_e32 v76, v64
	v_mov_b32_e32 v77, v64
	v_mov_b32_e32 v78, v64
	v_mov_b32_e32 v79, v64
	s_branch .LBB0_344

; template <bool DIFF> ...
;     ...
;             f32x2 ps2 = (f32x2){0.f, 0.f};
; #pragma unroll
;             for (int kb = 0; kb < 2; ++kb)
; #pragma unroll
;                 for (int r = 0; r < 16; r += 2) { const float e0 = __builtin_amdgcn_exp2f(pr[kb][r]), e1 = __builtin_amdgcn_exp2f(pr[kb][r + 1]); pr[kb][r] = e0; pr[kb][r + 1] = e1; ps2 += (f32x2){e0, e1}; }
;             lsum += ps2[0] + ps2[1];
;             __builtin_amdgcn_sched_barrier(0);
;             VLOAD(vfb, 1); __builtin_amdgcn_sched_barrier(0); PVMMA(vfa, 0); __builtin_amdgcn_sched_barrier(0);
;             VLOAD(vfa, 2); __builtin_amdgcn_sched_barrier(0); PVMMA(vfb, 1); __builtin_amdgcn_sched_barrier(0);
;             VLOAD(vfb, 3); __builtin_amdgcn_sched_barrier(0); PVMMA(vfa, 2); __builtin_amdgcn_sched_barrier(0);
;             PVMMA(vfb, 3);
;     ...
;         }
;         if (t + 1 < NT) ATT_LSTORE(buf ^ 1);
.LBB0_343:
.LBB0_344:
	v_exp_f32_e32 v236, v112
	v_exp_f32_e32 v237, v113
	v_exp_f32_e32 v112, v114
	v_exp_f32_e32 v113, v115
	v_pk_add_f32 v[222:223], v[236:237], 0 op_sel_hi:[1,0]
	v_exp_f32_e32 v114, v116
	v_exp_f32_e32 v115, v117
	v_pk_add_f32 v[222:223], v[112:113], v[222:223]
	v_exp_f32_e32 v116, v118
	v_exp_f32_e32 v117, v119
	v_pk_add_f32 v[222:223], v[114:115], v[222:223]
	v_cvt_pk_bf16_f32 v88, v236, v237
	v_cvt_pk_bf16_f32 v89, v112, v113
	v_cvt_pk_bf16_f32 v90, v114, v115
	v_cvt_pk_bf16_f32 v91, v116, v117
	s_setprio 1
	v_pk_add_f32 v[222:223], v[116:117], v[222:223]
	s_waitcnt lgkmcnt(8)
	v_mfma_f32_32x32x16_bf16 v[48:63], v[174:177], v[88:91], v[48:63]
	v_exp_f32_e32 v118, v120
	v_exp_f32_e32 v119, v121
	v_mfma_f32_32x32x16_bf16 v[32:47], v[170:173], v[88:91], v[32:47]
	v_exp_f32_e32 v120, v122
	v_exp_f32_e32 v121, v123
	v_pk_add_f32 v[222:223], v[118:119], v[222:223]
	v_mfma_f32_32x32x16_bf16 v[16:31], v[166:169], v[88:91], v[16:31]
	v_exp_f32_e32 v122, v124
	v_exp_f32_e32 v123, v125
	v_pk_add_f32 v[222:223], v[120:121], v[222:223]
	v_mfma_f32_32x32x16_bf16 v[0:15], v[162:165], v[88:91], v[0:15]
	v_exp_f32_e32 v124, v126
	v_exp_f32_e32 v125, v127
	v_pk_add_f32 v[222:223], v[122:123], v[222:223]
	ds_read_b64_tr_b16 v[162:163], v221 offset:27648
	ds_read_b64_tr_b16 v[166:167], v221 offset:27712
	ds_read_b64_tr_b16 v[170:171], v221 offset:27776
	ds_read_b64_tr_b16 v[174:175], v221 offset:27840
	ds_read_b64_tr_b16 v[164:165], v221 offset:30208
	ds_read_b64_tr_b16 v[168:169], v221 offset:30272
	ds_read_b64_tr_b16 v[172:173], v221 offset:30336
	ds_read_b64_tr_b16 v[176:177], v221 offset:30400
	v_cvt_pk_bf16_f32 v116, v118, v119
	v_cvt_pk_bf16_f32 v117, v120, v121
	v_cvt_pk_bf16_f32 v118, v122, v123
	v_cvt_pk_bf16_f32 v119, v124, v125
	v_pk_add_f32 v[222:223], v[124:125], v[222:223]
	s_waitcnt lgkmcnt(11)
	v_mfma_f32_32x32x16_bf16 v[48:63], v[224:227], v[116:119], v[48:63]
	v_exp_f32_e32 v126, v96
	v_exp_f32_e32 v127, v97
	s_waitcnt lgkmcnt(10)
	v_mfma_f32_32x32x16_bf16 v[32:47], v[228:231], v[116:119], v[32:47]
	v_exp_f32_e32 v198, v98
	v_exp_f32_e32 v199, v99
	v_pk_add_f32 v[222:223], v[126:127], v[222:223]
	s_waitcnt lgkmcnt(9)
	v_mfma_f32_32x32x16_bf16 v[16:31], v[232:235], v[116:119], v[16:31]
	v_exp_f32_e32 v238, v100
	v_exp_f32_e32 v239, v101
	v_pk_add_f32 v[222:223], v[198:199], v[222:223]
	s_waitcnt lgkmcnt(8)
	v_mfma_f32_32x32x16_bf16 v[0:15], v[92:95], v[116:119], v[0:15]
	v_exp_f32_e32 v240, v102
	v_exp_f32_e32 v241, v103
	v_pk_add_f32 v[222:223], v[238:239], v[222:223]
	ds_read_b64_tr_b16 v[224:225], v221 offset:32768
	ds_read_b64_tr_b16 v[228:229], v221 offset:32832
	ds_read_b64_tr_b16 v[232:233], v221 offset:32896
	ds_read_b64_tr_b16 v[92:93], v221 offset:32960
	ds_read_b64_tr_b16 v[226:227], v221 offset:35328
	ds_read_b64_tr_b16 v[230:231], v221 offset:35392
	ds_read_b64_tr_b16 v[234:235], v221 offset:35456
	ds_read_b64_tr_b16 v[94:95], v221 offset:35520
	v_cvt_pk_bf16_f32 v116, v126, v127
	v_cvt_pk_bf16_f32 v117, v198, v199
	v_cvt_pk_bf16_f32 v118, v238, v239
	v_cvt_pk_bf16_f32 v119, v240, v241
	v_pk_add_f32 v[222:223], v[240:241], v[222:223]
	s_waitcnt lgkmcnt(11)
	v_mfma_f32_32x32x16_bf16 v[48:63], v[162:165], v[116:119], v[48:63]
	v_exp_f32_e32 v242, v104
	v_exp_f32_e32 v243, v105
	s_waitcnt lgkmcnt(10)
	v_mfma_f32_32x32x16_bf16 v[32:47], v[166:169], v[116:119], v[32:47]
	v_exp_f32_e32 v244, v106
	v_exp_f32_e32 v245, v107
	v_pk_add_f32 v[222:223], v[242:243], v[222:223]
	s_waitcnt lgkmcnt(9)
	v_mfma_f32_32x32x16_bf16 v[16:31], v[170:173], v[116:119], v[16:31]
	v_exp_f32_e32 v246, v108
	v_exp_f32_e32 v247, v109
	v_pk_add_f32 v[222:223], v[244:245], v[222:223]
	s_waitcnt lgkmcnt(8)
	v_mfma_f32_32x32x16_bf16 v[0:15], v[174:177], v[116:119], v[0:15]
	v_exp_f32_e32 v248, v110
	v_exp_f32_e32 v249, v111
	v_pk_add_f32 v[222:223], v[246:247], v[222:223]
	s_xor_b32 s1, s0, 1
	s_mul_i32 s1, s1, 0x9400
	v_add3_u32 v96, s1, v206, v207
	v_add_u32_e32 v98, s1, v128
	v_add3_u32 v97, s1, v208, v210
	v_add_u32_e32 v99, v98, v211
	v_add_u32_e32 v98, v98, v212
	v_cvt_pk_bf16_f32 v100, v242, v243
	v_cvt_pk_bf16_f32 v101, v244, v245
	v_cvt_pk_bf16_f32 v102, v246, v247
	v_cvt_pk_bf16_f32 v103, v248, v249
	v_pk_add_f32 v[222:223], v[248:249], v[222:223]
	s_nop 0
	v_add_f32_e32 v84, v222, v223
	s_waitcnt lgkmcnt(3)
	v_mfma_f32_32x32x16_bf16 v[48:63], v[224:227], v[100:103], v[48:63]
	v_add_f32_e32 v187, v187, v84
	s_waitcnt vmcnt(3)
	ds_write_b128 v96, v[146:149]
	s_waitcnt lgkmcnt(3)
	v_mfma_f32_32x32x16_bf16 v[32:47], v[228:231], v[100:103], v[32:47]
	s_waitcnt vmcnt(2)
	ds_write_b128 v97, v[150:153]
	s_waitcnt lgkmcnt(3)
	v_mfma_f32_32x32x16_bf16 v[16:31], v[232:235], v[100:103], v[16:31]
	s_waitcnt vmcnt(1)
	ds_write_b128 v99, v[154:157] offset:17408
	s_waitcnt lgkmcnt(3)
	v_mfma_f32_32x32x16_bf16 v[0:15], v[92:95], v[100:103], v[0:15]
	s_waitcnt vmcnt(0)
	ds_write_b128 v98, v[158:161] offset:17408
	s_setprio 0
	s_branch .Ltail2_d1

; #define LAS __attribute__((address_space(3)))
; template <bool DIFF> ...
;     ...
;     for (int t = 0; t < NT; ++t) {
;         const int buf = t & 1;
;         if (t + 1 < NT) ATT_GLOAD(t + 1);
;         if (t < nt_w) {
;             const LAS unsigned char* kb_ = lds + buf * BUFB; const LAS unsigned char* vb_ = kb_ + KTILEB;
;             f32x16 pr[2];
;             const LAS unsigned char* vbase = vb_ + (4 * hi + ((lane & 15) >> 2)) * VROWB + (sdv + ((lane >> 4) & 1) * 16 + (lane & 3) * 4) * 2;
;     ...
;             bf16x8 vfa[NDB], vfb[NDB];
;             {
;                 bf16x8 kf[2][NS];
; #pragma unroll
;                 for (int kb = 0; kb < 2; ++kb)
; #pragma unroll
;                     for (int st = 0; st < NS; ++st) kf[kb][st] = *(const LAS bf16x8*)(kb_ + (kb * 32 + l32) * KROWB + (s * DQK + st * 16 + hi * 8) * 2);
;                 VLOAD(vfa, 0);
;                 __builtin_amdgcn_sched_barrier(0);
;                 __builtin_amdgcn_s_setprio(1);
; #pragma unroll
;                 for (int st = 0; st < NS; ++st) {
;                     pr[0] = __builtin_amdgcn_mfma_f32_32x32x16_bf16(kf[0][st], qf[st], st == 0 ? negm : pr[0], 0, 0, 0);
;                     pr[1] = __builtin_amdgcn_mfma_f32_32x32x16_bf16(kf[1][st], qf[st], st == 0 ? negm : pr[1], 0, 0, 0); }
;                 __builtin_amdgcn_s_setprio(0);
;             }
;             const int tp0 = (t == 0) ? -16 : (t - 1) * 64;
;             if (DIFF) {
;                 if (tp0 + 63 - qpos_w > -128) {
; #pragma unroll
;                     for (int kb = 0; kb < 2; ++kb)
; #pragma unroll
;                         for (int r = 0; r < 16; ++r) { const int kvi = kb * 32 + 8 * (r >> 2) + 4 * hi + (r & 3); int idx = tp0 + kvi - qpos + 128; idx = idx < 0 ? 0 : idx; pr[kb][r] += lut[idx]; }
;                 }
;             }
;     ...
;         if (t + 1 < NT) ATT_LSTORE(buf ^ 1);
;         __syncthreads();
.Ltail2_d1:
	s_add_i32 s45, s45, 1
	s_cmp_eq_u32 s31, s46
	s_cbranch_scc1 .Lxb_d1
	s_mov_b32 s47, s46
	s_cmp_lt_u32 s45, s35
	s_cbranch_scc0 .Lslow_d1
	s_and_b32 s0, s45, 1
	s_mul_i32 s1, s0, 0x9400
	v_add_u32_e32 v96, s1, v215
	v_add3_u32 v97, s1, v214, v213
	v_add_u32_e32 v221, v96, v209
	s_waitcnt lgkmcnt(0)
	s_barrier
	s_branch .Lbody_d1
.Lslow_d1:
	s_waitcnt lgkmcnt(0)
	s_barrier
	s_branch .LBB0_335
.Lxb_d1:
	s_waitcnt lgkmcnt(0)
	s_barrier
.LBB0_347:
	s_cmp_ge_u32 s45, s35
	s_cbranch_scc1 .LBB0_353
	s_add_i32 s0, s46, 64
	s_bitcmp1_b32 s45, 0
	s_cselect_b32 s1, 0x9400, 0
	s_add_i32 s1, s1, 0
	v_add_u32_e32 v112, s1, v215
	v_add3_u32 v113, s1, v214, v213
	v_add_u32_e32 v112, v112, v209
	ds_read_b128 v[114:117], v113
	ds_read_b128 v[118:121], v113 offset:32
	ds_read_b128 v[122:125], v113 offset:64
	ds_read_b128 v[146:149], v113 offset:96
	ds_read_b128 v[150:153], v113 offset:8704
	ds_read_b128 v[154:157], v113 offset:8736
	ds_read_b128 v[158:161], v113 offset:8768
	ds_read_b128 v[162:165], v113 offset:8800
	ds_read_b64_tr_b16 v[108:109], v112 offset:17408
	ds_read_b64_tr_b16 v[104:105], v112 offset:17472
	ds_read_b64_tr_b16 v[100:101], v112 offset:17536
	ds_read_b64_tr_b16 v[96:97], v112 offset:17600
	ds_read_b64_tr_b16 v[110:111], v112 offset:19968
	ds_read_b64_tr_b16 v[106:107], v112 offset:20032
	ds_read_b64_tr_b16 v[102:103], v112 offset:20096
	ds_read_b64_tr_b16 v[98:99], v112 offset:20160
	s_setprio 1
	s_waitcnt lgkmcnt(11)
	v_mfma_f32_32x32x16_bf16 v[80:95], v[150:153], v[142:145], v[64:79]
	s_nop 0
	v_mfma_f32_32x32x16_bf16 v[64:79], v[114:117], v[142:145], v[64:79]
	v_mfma_f32_32x32x16_bf16 v[64:79], v[118:121], v[138:141], v[64:79]
	s_waitcnt lgkmcnt(10)
	v_mfma_f32_32x32x16_bf16 v[80:95], v[154:157], v[138:141], v[80:95]
	v_mfma_f32_32x32x16_bf16 v[64:79], v[122:125], v[134:137], v[64:79]
	s_waitcnt lgkmcnt(9)
	v_mfma_f32_32x32x16_bf16 v[80:95], v[158:161], v[134:137], v[80:95]
	v_mfma_f32_32x32x16_bf16 v[64:79], v[146:149], v[130:133], v[64:79]
	s_waitcnt lgkmcnt(8)
	v_mfma_f32_32x32x16_bf16 v[80:95], v[162:165], v[130:133], v[80:95]
	s_setprio 0
	s_cmp_le_i32 s0, s44
	s_cbranch_scc1 .LBB0_350
	v_add_u32_e32 v113, s0, v205
	v_subrev_u32_e32 v113, 64, v113
	s_add_i32 s0, 0, 0x18000
	v_max_i32_e32 v132, 0xffffff5f, v113
	v_lshl_add_u32 v133, v132, 2, s0
	v_max_i32_e32 v132, 0xffffff5e, v113
	v_lshl_add_u32 v134, v132, 2, s0
	v_max_i32_e32 v132, 0xffffff5d, v113
	v_lshl_add_u32 v135, v132, 2, s0
	v_max_i32_e32 v132, 0xffffff58, v113
	v_max_i32_e32 v140, 0xffffff4f, v113
	v_max_i32_e32 v114, 0xffffff80, v113
	v_max_i32_e32 v115, 0xffffff7f, v113
	v_max_i32_e32 v116, 0xffffff7e, v113
	v_max_i32_e32 v117, 0xffffff7d, v113
	v_max_i32_e32 v118, 0xffffff78, v113
	v_max_i32_e32 v119, 0xffffff77, v113
	v_max_i32_e32 v120, 0xffffff76, v113
	v_max_i32_e32 v121, 0xffffff75, v113
	v_max_i32_e32 v122, 0xffffff70, v113
	v_max_i32_e32 v123, 0xffffff6f, v113
	v_max_i32_e32 v124, 0xffffff6e, v113
	v_max_i32_e32 v125, 0xffffff6d, v113
	v_max_i32_e32 v126, 0xffffff68, v113
	v_max_i32_e32 v127, 0xffffff67, v113
	v_max_i32_e32 v128, 0xffffff66, v113
	v_max_i32_e32 v130, 0xffffff65, v113
	v_lshl_add_u32 v136, v132, 2, s0
	v_max_i32_e32 v132, 0xffffff57, v113
	v_lshl_add_u32 v141, v140, 2, s0
	v_max_i32_e32 v140, 0xffffff4e, v113
	v_lshl_add_u32 v114, v114, 2, s0
	v_lshl_add_u32 v115, v115, 2, s0
	v_lshl_add_u32 v116, v116, 2, s0
	v_lshl_add_u32 v117, v117, 2, s0
	v_lshl_add_u32 v118, v118, 2, s0
	v_lshl_add_u32 v119, v119, 2, s0
	v_lshl_add_u32 v120, v120, 2, s0
	v_lshl_add_u32 v121, v121, 2, s0
	v_lshl_add_u32 v122, v122, 2, s0
	v_lshl_add_u32 v123, v123, 2, s0
	v_lshl_add_u32 v124, v124, 2, s0
	v_lshl_add_u32 v125, v125, 2, s0
	v_lshl_add_u32 v126, v126, 2, s0
	v_lshl_add_u32 v127, v127, 2, s0
	v_lshl_add_u32 v128, v128, 2, s0
	v_lshl_add_u32 v131, v130, 2, s0
	v_lshl_add_u32 v137, v132, 2, s0
	v_max_i32_e32 v132, 0xffffff56, v113
	v_lshl_add_u32 v142, v140, 2, s0
	v_max_i32_e32 v140, 0xffffff4d, v113
	ds_read_b32 v114, v114 offset:512
	ds_read_b32 v115, v115 offset:516
	ds_read_b32 v116, v116 offset:520
	ds_read_b32 v117, v117 offset:524
	ds_read_b32 v118, v118 offset:544
	ds_read_b32 v119, v119 offset:548
	ds_read_b32 v120, v120 offset:552
	ds_read_b32 v121, v121 offset:556
	ds_read_b32 v122, v122 offset:576
	ds_read_b32 v123, v123 offset:580
	ds_read_b32 v124, v124 offset:584
	ds_read_b32 v125, v125 offset:588
	ds_read_b32 v126, v126 offset:608
	ds_read_b32 v127, v127 offset:612
	ds_read_b32 v130, v128 offset:616
	ds_read_b32 v131, v131 offset:620
	v_max_i32_e32 v128, 0xffffff60, v113
	v_lshl_add_u32 v138, v132, 2, s0
	v_max_i32_e32 v132, 0xffffff55, v113
	v_lshl_add_u32 v143, v140, 2, s0
	v_max_i32_e32 v140, 0xffffff48, v113
	v_lshl_add_u32 v128, v128, 2, s0
	v_lshl_add_u32 v139, v132, 2, s0
	v_lshl_add_u32 v144, v140, 2, s0
	v_max_i32_e32 v140, 0xffffff47, v113
	ds_read_b32 v132, v128 offset:640
	ds_read_b32 v133, v133 offset:644
	ds_read_b32 v134, v134 offset:648
	ds_read_b32 v135, v135 offset:652
	ds_read_b32 v136, v136 offset:672
	ds_read_b32 v137, v137 offset:676
	ds_read_b32 v138, v138 offset:680
	ds_read_b32 v139, v139 offset:684
	v_max_i32_e32 v128, 0xffffff50, v113
	v_lshl_add_u32 v145, v140, 2, s0
	v_max_i32_e32 v140, 0xffffff46, v113
	v_lshl_add_u32 v128, v128, 2, s0
	v_lshl_add_u32 v146, v140, 2, s0
	v_max_i32_e32 v113, 0xffffff45, v113
	v_lshl_add_u32 v113, v113, 2, s0
	ds_read_b32 v140, v128 offset:704
	ds_read_b32 v141, v141 offset:708
	ds_read_b32 v142, v142 offset:712
	ds_read_b32 v143, v143 offset:716
	ds_read_b32 v144, v144 offset:736
	ds_read_b32 v145, v145 offset:740
	ds_read_b32 v146, v146 offset:744
	ds_read_b32 v147, v113 offset:748
	s_waitcnt lgkmcnt(14)
	v_pk_add_f32 v[78:79], v[78:79], v[130:131]
	v_pk_add_f32 v[76:77], v[76:77], v[126:127]
	v_pk_add_f32 v[74:75], v[74:75], v[124:125]
	v_pk_add_f32 v[72:73], v[72:73], v[122:123]
	v_pk_add_f32 v[70:71], v[70:71], v[120:121]
	v_pk_add_f32 v[68:69], v[68:69], v[118:119]
	v_pk_add_f32 v[66:67], v[66:67], v[116:117]
	v_pk_add_f32 v[64:65], v[64:65], v[114:115]
	s_waitcnt lgkmcnt(0)
	v_pk_add_f32 v[94:95], v[94:95], v[146:147]
	v_pk_add_f32 v[92:93], v[92:93], v[144:145]
	v_pk_add_f32 v[90:91], v[90:91], v[142:143]
	v_pk_add_f32 v[88:89], v[88:89], v[140:141]
	v_pk_add_f32 v[86:87], v[86:87], v[138:139]
	v_pk_add_f32 v[84:85], v[84:85], v[136:137]
	v_pk_add_f32 v[82:83], v[82:83], v[134:135]
	v_pk_add_f32 v[80:81], v[80:81], v[132:133]

; #define LAS __attribute__((address_space(3)))
; template <bool DIFF> ...
;     ...
;     for (int t = 0; t < NT; ++t) {
;         const int buf = t & 1;
;         if (t + 1 < NT) ATT_GLOAD(t + 1);
;         if (t < nt_w) {
;             const LAS unsigned char* kb_ = lds + buf * BUFB; const LAS unsigned char* vb_ = kb_ + KTILEB;
;             f32x16 pr[2];
;             const LAS unsigned char* vbase = vb_ + (4 * hi + ((lane & 15) >> 2)) * VROWB + (sdv + ((lane >> 4) & 1) * 16 + (lane & 3) * 4) * 2;
;     ...
;             bf16x8 vfa[NDB], vfb[NDB];
;             {
;                 bf16x8 kf[2][NS];
; #pragma unroll
;                 for (int kb = 0; kb < 2; ++kb)
; #pragma unroll
;                     for (int st = 0; st < NS; ++st) kf[kb][st] = *(const LAS bf16x8*)(kb_ + (kb * 32 + l32) * KROWB + (s * DQK + st * 16 + hi * 8) * 2);
;                 VLOAD(vfa, 0);
;                 __builtin_amdgcn_sched_barrier(0);
;                 __builtin_amdgcn_s_setprio(1);
; #pragma unroll
;                 for (int st = 0; st < NS; ++st) {
;                     pr[0] = __builtin_amdgcn_mfma_f32_32x32x16_bf16(kf[0][st], qf[st], st == 0 ? negm : pr[0], 0, 0, 0);
;                     pr[1] = __builtin_amdgcn_mfma_f32_32x32x16_bf16(kf[1][st], qf[st], st == 0 ? negm : pr[1], 0, 0, 0); }
;                 __builtin_amdgcn_s_setprio(0);
;             }
;             const int tp0 = (t == 0) ? -16 : (t - 1) * 64;
;             if (DIFF) {
;                 if (tp0 + 63 - qpos_w > -128) {
; #pragma unroll
;                     for (int kb = 0; kb < 2; ++kb)
; #pragma unroll
;                         for (int r = 0; r < 16; ++r) { const int kvi = kb * 32 + 8 * (r >> 2) + 4 * hi + (r & 3); int idx = tp0 + kvi - qpos + 128; idx = idx < 0 ? 0 : idx; pr[kb][r] += lut[idx]; }
;                 }
;             }
.Lbody_d2:
	ds_read_b128 v[80:83], v97
	ds_read_b128 v[84:87], v97 offset:32
	ds_read_b128 v[88:91], v97 offset:64
	ds_read_b128 v[92:95], v97 offset:96
	ds_read_b128 v[222:225], v97 offset:8704
	ds_read_b128 v[226:229], v97 offset:8736
	ds_read_b128 v[230:233], v97 offset:8768
	ds_read_b128 v[234:237], v97 offset:8800
	ds_read_b64_tr_b16 v[174:175], v221 offset:17408
	ds_read_b64_tr_b16 v[170:171], v221 offset:17472
	ds_read_b64_tr_b16 v[166:167], v221 offset:17536
	ds_read_b64_tr_b16 v[162:163], v221 offset:17600
	ds_read_b64_tr_b16 v[176:177], v221 offset:19968
	ds_read_b64_tr_b16 v[172:173], v221 offset:20032
	ds_read_b64_tr_b16 v[168:169], v221 offset:20096
	ds_read_b64_tr_b16 v[164:165], v221 offset:20160
	s_setprio 1
	s_waitcnt lgkmcnt(14)
	v_mfma_f32_32x32x16_bf16 v[112:127], v[80:83], v[142:145], v[64:79]
	s_waitcnt lgkmcnt(11)
	v_mfma_f32_32x32x16_bf16 v[96:111], v[222:225], v[142:145], v[64:79]
	v_add_u32_e32 v80, s35, v220
	v_ashrrev_i32_e32 v81, 31, v80
	v_add_u32_e32 v82, s35, v219
	v_lshlrev_b64 v[80:81], 11, v[80:81]
	v_mfma_f32_32x32x16_bf16 v[112:127], v[84:87], v[138:141], v[112:127]
	v_ashrrev_i32_e32 v83, 31, v82
	v_lshl_add_u64 v[80:81], v[190:191], 0, v[80:81]
	v_lshlrev_b64 v[82:83], 11, v[82:83]
	v_lshl_add_u64 v[82:83], v[192:193], 0, v[82:83]
	global_load_dwordx4 v[146:149], v[80:81], off
	global_load_dwordx4 v[150:153], v[82:83], off
	s_waitcnt lgkmcnt(10)
	v_mfma_f32_32x32x16_bf16 v[96:111], v[226:229], v[138:141], v[96:111]
	v_add_u32_e32 v80, s35, v218
	v_ashrrev_i32_e32 v81, 31, v80
	v_add_u32_e32 v82, s35, v217
	v_lshlrev_b64 v[80:81], 11, v[80:81]
	v_mfma_f32_32x32x16_bf16 v[112:127], v[88:91], v[134:137], v[112:127]
	v_ashrrev_i32_e32 v83, 31, v82
	v_lshl_add_u64 v[80:81], v[188:189], 0, v[80:81]
	v_lshlrev_b64 v[82:83], 11, v[82:83]
	v_lshl_add_u64 v[82:83], v[188:189], 0, v[82:83]
	global_load_dwordx4 v[154:157], v[80:81], off
	global_load_dwordx4 v[158:161], v[82:83], off
	s_waitcnt lgkmcnt(9)
	v_mfma_f32_32x32x16_bf16 v[96:111], v[230:233], v[134:137], v[96:111]
	v_mfma_f32_32x32x16_bf16 v[112:127], v[92:95], v[130:133], v[112:127]
	s_waitcnt lgkmcnt(8)
	v_mfma_f32_32x32x16_bf16 v[96:111], v[234:237], v[130:133], v[96:111]
	s_setprio 0
	s_add_i32 s20, s35, 64
	s_cmp_le_u32 s20, s30
	s_cbranch_scc1 .LBB0_365
	v_add_u32_e32 v200, s35, v216
	s_add_i32 s1, 0, 0x18000
	v_max_i32_e32 v222, 0xffffff5d, v200
	v_lshl_add_u32 v223, v222, 2, s1
	v_max_i32_e32 v222, 0xffffff58, v200
	v_max_i32_e32 v228, 0xffffff4f, v200
	v_lshl_add_u32 v224, v222, 2, s1
	v_max_i32_e32 v222, 0xffffff57, v200
	v_lshl_add_u32 v229, v228, 2, s1
	v_max_i32_e32 v228, 0xffffff4e, v200
	v_lshl_add_u32 v225, v222, 2, s1
	v_max_i32_e32 v222, 0xffffff56, v200
	v_lshl_add_u32 v230, v228, 2, s1
	v_max_i32_e32 v228, 0xffffff4d, v200
	v_max_i32_e32 v80, 0xffffff80, v200
	v_max_i32_e32 v81, 0xffffff7f, v200
	v_max_i32_e32 v82, 0xffffff7e, v200
	v_max_i32_e32 v83, 0xffffff7d, v200
	v_max_i32_e32 v84, 0xffffff78, v200
	v_max_i32_e32 v85, 0xffffff77, v200
	v_max_i32_e32 v86, 0xffffff76, v200
	v_max_i32_e32 v87, 0xffffff75, v200
	v_max_i32_e32 v88, 0xffffff70, v200
	v_max_i32_e32 v89, 0xffffff6f, v200
	v_max_i32_e32 v90, 0xffffff6e, v200
	v_max_i32_e32 v91, 0xffffff6d, v200
	v_max_i32_e32 v92, 0xffffff68, v200
	v_max_i32_e32 v93, 0xffffff67, v200
	v_max_i32_e32 v94, 0xffffff66, v200
	v_max_i32_e32 v95, 0xffffff65, v200
	v_max_i32_e32 v198, 0xffffff60, v200
	v_max_i32_e32 v199, 0xffffff5f, v200
	v_max_i32_e32 v201, 0xffffff5e, v200
	v_lshl_add_u32 v226, v222, 2, s1
	v_max_i32_e32 v222, 0xffffff55, v200
	v_lshl_add_u32 v231, v228, 2, s1
	v_max_i32_e32 v228, 0xffffff48, v200
	v_lshl_add_u32 v80, v80, 2, s1
	v_lshl_add_u32 v81, v81, 2, s1
	v_lshl_add_u32 v82, v82, 2, s1
	v_lshl_add_u32 v83, v83, 2, s1
	v_lshl_add_u32 v84, v84, 2, s1
	v_lshl_add_u32 v85, v85, 2, s1
	v_lshl_add_u32 v86, v86, 2, s1
	v_lshl_add_u32 v87, v87, 2, s1
	v_lshl_add_u32 v88, v88, 2, s1
	v_lshl_add_u32 v89, v89, 2, s1
	v_lshl_add_u32 v90, v90, 2, s1
	v_lshl_add_u32 v91, v91, 2, s1
	v_lshl_add_u32 v92, v92, 2, s1
	v_lshl_add_u32 v93, v93, 2, s1
	v_lshl_add_u32 v94, v94, 2, s1
	v_lshl_add_u32 v95, v95, 2, s1
	v_lshl_add_u32 v198, v198, 2, s1
	v_lshl_add_u32 v199, v199, 2, s1
	v_lshl_add_u32 v201, v201, 2, s1
	v_lshl_add_u32 v227, v222, 2, s1
	v_lshl_add_u32 v232, v228, 2, s1
	v_max_i32_e32 v228, 0xffffff47, v200
	ds_read_b32 v80, v80 offset:512
	ds_read_b32 v81, v81 offset:516
	ds_read_b32 v82, v82 offset:520
	ds_read_b32 v83, v83 offset:524
	ds_read_b32 v84, v84 offset:544
	ds_read_b32 v85, v85 offset:548
	ds_read_b32 v86, v86 offset:552
	ds_read_b32 v87, v87 offset:556
	ds_read_b32 v88, v88 offset:576
	ds_read_b32 v89, v89 offset:580
	ds_read_b32 v90, v90 offset:584
	ds_read_b32 v91, v91 offset:588
	ds_read_b32 v92, v92 offset:608
	ds_read_b32 v93, v93 offset:612
	ds_read_b32 v94, v94 offset:616
	ds_read_b32 v95, v95 offset:620
	ds_read_b32 v198, v198 offset:640
	ds_read_b32 v199, v199 offset:644
	ds_read_b32 v222, v201 offset:648
	ds_read_b32 v223, v223 offset:652
	ds_read_b32 v224, v224 offset:672
	ds_read_b32 v225, v225 offset:676
	ds_read_b32 v226, v226 offset:680
	ds_read_b32 v227, v227 offset:684
	v_max_i32_e32 v201, 0xffffff50, v200
	v_lshl_add_u32 v233, v228, 2, s1
	v_max_i32_e32 v228, 0xffffff46, v200
	v_lshl_add_u32 v201, v201, 2, s1
	v_lshl_add_u32 v234, v228, 2, s1
	v_max_i32_e32 v200, 0xffffff45, v200
	v_lshl_add_u32 v200, v200, 2, s1
	ds_read_b32 v228, v201 offset:704
	ds_read_b32 v229, v229 offset:708
	ds_read_b32 v230, v230 offset:712
	ds_read_b32 v231, v231 offset:716
	ds_read_b32 v232, v232 offset:736
	ds_read_b32 v233, v233 offset:740
	ds_read_b32 v234, v234 offset:744
	ds_read_b32 v235, v200 offset:748
	s_waitcnt lgkmcnt(14)
	v_pk_add_f32 v[126:127], v[126:127], v[94:95]
	v_pk_add_f32 v[124:125], v[124:125], v[92:93]
	v_pk_add_f32 v[122:123], v[122:123], v[90:91]
	v_pk_add_f32 v[120:121], v[120:121], v[88:89]
	v_pk_add_f32 v[118:119], v[118:119], v[86:87]
	v_pk_add_f32 v[116:117], v[116:117], v[84:85]
	v_pk_add_f32 v[114:115], v[114:115], v[82:83]
	v_pk_add_f32 v[112:113], v[112:113], v[80:81]
	s_waitcnt lgkmcnt(0)
	v_pk_add_f32 v[110:111], v[110:111], v[234:235]
	v_pk_add_f32 v[108:109], v[108:109], v[232:233]
	v_pk_add_f32 v[106:107], v[106:107], v[230:231]
	v_pk_add_f32 v[104:105], v[104:105], v[228:229]
	v_pk_add_f32 v[102:103], v[102:103], v[226:227]
	v_pk_add_f32 v[100:101], v[100:101], v[224:225]
	v_pk_add_f32 v[98:99], v[98:99], v[222:223]
	v_pk_add_f32 v[96:97], v[96:97], v[198:199]

; template <bool DIFF> ...
;     ...
;             f32x2 ps2 = (f32x2){0.f, 0.f};
; #pragma unroll
;             for (int kb = 0; kb < 2; ++kb)
; #pragma unroll
;                 for (int r = 0; r < 16; r += 2) { const float e0 = __builtin_amdgcn_exp2f(pr[kb][r]), e1 = __builtin_amdgcn_exp2f(pr[kb][r + 1]); pr[kb][r] = e0; pr[kb][r + 1] = e1; ps2 += (f32x2){e0, e1}; }
;             lsum += ps2[0] + ps2[1];
;             __builtin_amdgcn_sched_barrier(0);
;             VLOAD(vfb, 1); __builtin_amdgcn_sched_barrier(0); PVMMA(vfa, 0); __builtin_amdgcn_sched_barrier(0);
;             VLOAD(vfa, 2); __builtin_amdgcn_sched_barrier(0); PVMMA(vfb, 1); __builtin_amdgcn_sched_barrier(0);
;             VLOAD(vfb, 3); __builtin_amdgcn_sched_barrier(0); PVMMA(vfa, 2); __builtin_amdgcn_sched_barrier(0);
;             PVMMA(vfb, 3);
;     ...
;         }
;         if (t + 1 < NT) ATT_LSTORE(buf ^ 1);
.LBB0_368:
.LBB0_369:
	v_exp_f32_e32 v236, v112
	v_exp_f32_e32 v237, v113
	v_exp_f32_e32 v112, v114
	v_exp_f32_e32 v113, v115
	v_pk_add_f32 v[222:223], v[236:237], 0 op_sel_hi:[1,0]
	v_exp_f32_e32 v114, v116
	v_exp_f32_e32 v115, v117
	v_pk_add_f32 v[222:223], v[112:113], v[222:223]
	v_exp_f32_e32 v116, v118
	v_exp_f32_e32 v117, v119
	v_pk_add_f32 v[222:223], v[114:115], v[222:223]
	v_cvt_pk_bf16_f32 v88, v236, v237
	v_cvt_pk_bf16_f32 v89, v112, v113
	v_cvt_pk_bf16_f32 v90, v114, v115
	v_cvt_pk_bf16_f32 v91, v116, v117
	s_setprio 1
	v_pk_add_f32 v[222:223], v[116:117], v[222:223]
	s_waitcnt lgkmcnt(8)
	v_mfma_f32_32x32x16_bf16 v[48:63], v[174:177], v[88:91], v[48:63]
	v_exp_f32_e32 v118, v120
	v_exp_f32_e32 v119, v121
	v_mfma_f32_32x32x16_bf16 v[32:47], v[170:173], v[88:91], v[32:47]
	v_exp_f32_e32 v120, v122
	v_exp_f32_e32 v121, v123
	v_pk_add_f32 v[222:223], v[118:119], v[222:223]
	v_mfma_f32_32x32x16_bf16 v[16:31], v[166:169], v[88:91], v[16:31]
	v_exp_f32_e32 v122, v124
	v_exp_f32_e32 v123, v125
	v_pk_add_f32 v[222:223], v[120:121], v[222:223]
	v_mfma_f32_32x32x16_bf16 v[0:15], v[162:165], v[88:91], v[0:15]
	v_exp_f32_e32 v124, v126
	v_exp_f32_e32 v125, v127
	v_pk_add_f32 v[222:223], v[122:123], v[222:223]
	ds_read_b64_tr_b16 v[162:163], v221 offset:27648
	ds_read_b64_tr_b16 v[166:167], v221 offset:27712
	ds_read_b64_tr_b16 v[170:171], v221 offset:27776
	ds_read_b64_tr_b16 v[174:175], v221 offset:27840
	ds_read_b64_tr_b16 v[164:165], v221 offset:30208
	ds_read_b64_tr_b16 v[168:169], v221 offset:30272
	ds_read_b64_tr_b16 v[172:173], v221 offset:30336
	ds_read_b64_tr_b16 v[176:177], v221 offset:30400
	v_cvt_pk_bf16_f32 v116, v118, v119
	v_cvt_pk_bf16_f32 v117, v120, v121
	v_cvt_pk_bf16_f32 v118, v122, v123
	v_cvt_pk_bf16_f32 v119, v124, v125
	v_pk_add_f32 v[222:223], v[124:125], v[222:223]
	s_waitcnt lgkmcnt(11)
	v_mfma_f32_32x32x16_bf16 v[48:63], v[224:227], v[116:119], v[48:63]
	v_exp_f32_e32 v126, v96
	v_exp_f32_e32 v127, v97
	s_waitcnt lgkmcnt(10)
	v_mfma_f32_32x32x16_bf16 v[32:47], v[228:231], v[116:119], v[32:47]
	v_exp_f32_e32 v198, v98
	v_exp_f32_e32 v199, v99
	v_pk_add_f32 v[222:223], v[126:127], v[222:223]
	s_waitcnt lgkmcnt(9)
	v_mfma_f32_32x32x16_bf16 v[16:31], v[232:235], v[116:119], v[16:31]
	v_exp_f32_e32 v238, v100
	v_exp_f32_e32 v239, v101
	v_pk_add_f32 v[222:223], v[198:199], v[222:223]
	s_waitcnt lgkmcnt(8)
	v_mfma_f32_32x32x16_bf16 v[0:15], v[92:95], v[116:119], v[0:15]
	v_exp_f32_e32 v240, v102
	v_exp_f32_e32 v241, v103
	v_pk_add_f32 v[222:223], v[238:239], v[222:223]
	ds_read_b64_tr_b16 v[224:225], v221 offset:32768
	ds_read_b64_tr_b16 v[228:229], v221 offset:32832
	ds_read_b64_tr_b16 v[232:233], v221 offset:32896
	ds_read_b64_tr_b16 v[92:93], v221 offset:32960
	ds_read_b64_tr_b16 v[226:227], v221 offset:35328
	ds_read_b64_tr_b16 v[230:231], v221 offset:35392
	ds_read_b64_tr_b16 v[234:235], v221 offset:35456
	ds_read_b64_tr_b16 v[94:95], v221 offset:35520
	v_cvt_pk_bf16_f32 v116, v126, v127
	v_cvt_pk_bf16_f32 v117, v198, v199
	v_cvt_pk_bf16_f32 v118, v238, v239
	v_cvt_pk_bf16_f32 v119, v240, v241
	v_pk_add_f32 v[222:223], v[240:241], v[222:223]
	s_waitcnt lgkmcnt(11)
	v_mfma_f32_32x32x16_bf16 v[48:63], v[162:165], v[116:119], v[48:63]
	v_exp_f32_e32 v242, v104
	v_exp_f32_e32 v243, v105
	s_waitcnt lgkmcnt(10)
	v_mfma_f32_32x32x16_bf16 v[32:47], v[166:169], v[116:119], v[32:47]
	v_exp_f32_e32 v244, v106
	v_exp_f32_e32 v245, v107
	v_pk_add_f32 v[222:223], v[242:243], v[222:223]
	s_waitcnt lgkmcnt(9)
	v_mfma_f32_32x32x16_bf16 v[16:31], v[170:173], v[116:119], v[16:31]
	v_exp_f32_e32 v246, v108
	v_exp_f32_e32 v247, v109
	v_pk_add_f32 v[222:223], v[244:245], v[222:223]
	s_waitcnt lgkmcnt(8)
	v_mfma_f32_32x32x16_bf16 v[0:15], v[174:177], v[116:119], v[0:15]
	v_exp_f32_e32 v248, v110
	v_exp_f32_e32 v249, v111
	v_pk_add_f32 v[222:223], v[246:247], v[222:223]
	s_xor_b32 s1, s0, 1
	s_mul_i32 s1, s1, 0x9400
	v_add3_u32 v96, s1, v206, v207
	v_add_u32_e32 v98, s1, v128
	v_add3_u32 v97, s1, v208, v209
	v_add_u32_e32 v99, v98, v210
	v_add_u32_e32 v98, v98, v211
	v_cvt_pk_bf16_f32 v100, v242, v243
	v_cvt_pk_bf16_f32 v101, v244, v245
	v_cvt_pk_bf16_f32 v102, v246, v247
	v_cvt_pk_bf16_f32 v103, v248, v249
	v_pk_add_f32 v[222:223], v[248:249], v[222:223]
	s_nop 0
	v_add_f32_e32 v84, v222, v223
	s_waitcnt lgkmcnt(3)
	v_mfma_f32_32x32x16_bf16 v[48:63], v[224:227], v[100:103], v[48:63]
	v_add_f32_e32 v187, v187, v84
	s_waitcnt vmcnt(3)
	ds_write_b128 v96, v[146:149]
	s_waitcnt lgkmcnt(3)
	v_mfma_f32_32x32x16_bf16 v[32:47], v[228:231], v[100:103], v[32:47]
	s_waitcnt vmcnt(2)
	ds_write_b128 v97, v[150:153]
	s_waitcnt lgkmcnt(3)
	v_mfma_f32_32x32x16_bf16 v[16:31], v[232:235], v[100:103], v[16:31]
	s_waitcnt vmcnt(1)
	ds_write_b128 v99, v[154:157] offset:17408
	s_waitcnt lgkmcnt(3)
	v_mfma_f32_32x32x16_bf16 v[0:15], v[92:95], v[100:103], v[0:15]
	s_waitcnt vmcnt(0)
	ds_write_b128 v98, v[158:161] offset:17408
	s_setprio 0
	s_branch .Ltail2_d2

; #define LAS __attribute__((address_space(3)))
; template <bool DIFF> ...
;     ...
;     for (int t = 0; t < NT; ++t) {
;         const int buf = t & 1;
;         if (t + 1 < NT) ATT_GLOAD(t + 1);
;         if (t < nt_w) {
;             const LAS unsigned char* kb_ = lds + buf * BUFB; const LAS unsigned char* vb_ = kb_ + KTILEB;
;             f32x16 pr[2];
;             const LAS unsigned char* vbase = vb_ + (4 * hi + ((lane & 15) >> 2)) * VROWB + (sdv + ((lane >> 4) & 1) * 16 + (lane & 3) * 4) * 2;
;     ...
;             bf16x8 vfa[NDB], vfb[NDB];
;             {
;                 bf16x8 kf[2][NS];
; #pragma unroll
;                 for (int kb = 0; kb < 2; ++kb)
; #pragma unroll
;                     for (int st = 0; st < NS; ++st) kf[kb][st] = *(const LAS bf16x8*)(kb_ + (kb * 32 + l32) * KROWB + (s * DQK + st * 16 + hi * 8) * 2);
;                 VLOAD(vfa, 0);
;                 __builtin_amdgcn_sched_barrier(0);
;                 __builtin_amdgcn_s_setprio(1);
; #pragma unroll
;                 for (int st = 0; st < NS; ++st) {
;                     pr[0] = __builtin_amdgcn_mfma_f32_32x32x16_bf16(kf[0][st], qf[st], st == 0 ? negm : pr[0], 0, 0, 0);
;                     pr[1] = __builtin_amdgcn_mfma_f32_32x32x16_bf16(kf[1][st], qf[st], st == 0 ? negm : pr[1], 0, 0, 0); }
;                 __builtin_amdgcn_s_setprio(0);
;             }
;             const int tp0 = (t == 0) ? -16 : (t - 1) * 64;
;             if (DIFF) {
;                 if (tp0 + 63 - qpos_w > -128) {
; #pragma unroll
;                     for (int kb = 0; kb < 2; ++kb)
; #pragma unroll
;                         for (int r = 0; r < 16; ++r) { const int kvi = kb * 32 + 8 * (r >> 2) + 4 * hi + (r & 3); int idx = tp0 + kvi - qpos + 128; idx = idx < 0 ? 0 : idx; pr[kb][r] += lut[idx]; }
;                 }
;     ...
;         if (t + 1 < NT) ATT_LSTORE(buf ^ 1);
;         __syncthreads();
.Ltail2_d2:
	s_add_i32 s26, s26, 1
	s_cmp_eq_u32 s31, s20
	s_cbranch_scc1 .Lxb_d2
	s_mov_b32 s35, s20
	s_cmp_lt_u32 s26, s28
	s_cbranch_scc0 .Lslow_d2
	s_and_b32 s0, s26, 1
	s_mul_i32 s1, s0, 0x9400
	v_add_u32_e32 v96, s1, v213
	v_add3_u32 v97, s1, v215, v214
	v_add_u32_e32 v221, v96, v212
	s_waitcnt lgkmcnt(0)
	s_barrier
	s_branch .Lbody_d2
.Lslow_d2:
	s_waitcnt lgkmcnt(0)
	s_barrier
	s_branch .LBB0_360
.Lxb_d2:
	s_waitcnt lgkmcnt(0)
	s_barrier
.LBB0_372:
	s_cmp_ge_u32 s26, s28
	s_cbranch_scc1 .LBB0_378
	s_add_i32 s0, s20, 64
	s_bitcmp1_b32 s26, 0
	s_cselect_b32 s1, 0x9400, 0
	s_add_i32 s1, s1, 0
	v_add_u32_e32 v112, s1, v213
	v_add3_u32 v113, s1, v215, v214
	v_add_u32_e32 v112, v112, v212
	ds_read_b128 v[114:117], v113
	ds_read_b128 v[118:121], v113 offset:32
	ds_read_b128 v[122:125], v113 offset:64
	ds_read_b128 v[146:149], v113 offset:96
	ds_read_b128 v[150:153], v113 offset:8704
	ds_read_b128 v[154:157], v113 offset:8736
	ds_read_b128 v[158:161], v113 offset:8768
	ds_read_b128 v[162:165], v113 offset:8800
	ds_read_b64_tr_b16 v[108:109], v112 offset:17408
	ds_read_b64_tr_b16 v[104:105], v112 offset:17472
	ds_read_b64_tr_b16 v[100:101], v112 offset:17536
	ds_read_b64_tr_b16 v[96:97], v112 offset:17600
	ds_read_b64_tr_b16 v[110:111], v112 offset:19968
	ds_read_b64_tr_b16 v[106:107], v112 offset:20032
	ds_read_b64_tr_b16 v[102:103], v112 offset:20096
	ds_read_b64_tr_b16 v[98:99], v112 offset:20160
	s_setprio 1
	s_waitcnt lgkmcnt(11)
	v_mfma_f32_32x32x16_bf16 v[80:95], v[150:153], v[142:145], v[64:79]
	s_nop 0
	v_mfma_f32_32x32x16_bf16 v[64:79], v[114:117], v[142:145], v[64:79]
	v_mfma_f32_32x32x16_bf16 v[64:79], v[118:121], v[138:141], v[64:79]
	s_waitcnt lgkmcnt(10)
	v_mfma_f32_32x32x16_bf16 v[80:95], v[154:157], v[138:141], v[80:95]
	v_mfma_f32_32x32x16_bf16 v[64:79], v[122:125], v[134:137], v[64:79]
	s_waitcnt lgkmcnt(9)
	v_mfma_f32_32x32x16_bf16 v[80:95], v[158:161], v[134:137], v[80:95]
	v_mfma_f32_32x32x16_bf16 v[64:79], v[146:149], v[130:133], v[64:79]
	s_waitcnt lgkmcnt(8)
	v_mfma_f32_32x32x16_bf16 v[80:95], v[162:165], v[130:133], v[80:95]
	s_setprio 0
	s_cmp_le_u32 s0, s30
	s_cbranch_scc1 .LBB0_375
	v_or_b32_e32 v113, s27, v205
	v_sub_u32_e32 v113, v203, v113
	v_add_u32_e32 v113, s0, v113
	v_subrev_u32_e32 v113, 64, v113
	s_add_i32 s0, 0, 0x18000
	v_max_i32_e32 v132, 0xffffff5f, v113
	v_lshl_add_u32 v133, v132, 2, s0
	v_max_i32_e32 v132, 0xffffff5e, v113
	v_lshl_add_u32 v134, v132, 2, s0
	v_max_i32_e32 v132, 0xffffff5d, v113
	v_lshl_add_u32 v135, v132, 2, s0
	v_max_i32_e32 v132, 0xffffff58, v113
	v_max_i32_e32 v140, 0xffffff4f, v113
	v_max_i32_e32 v114, 0xffffff80, v113
	v_max_i32_e32 v115, 0xffffff7f, v113
	v_max_i32_e32 v116, 0xffffff7e, v113
	v_max_i32_e32 v117, 0xffffff7d, v113
	v_max_i32_e32 v118, 0xffffff78, v113
	v_max_i32_e32 v119, 0xffffff77, v113
	v_max_i32_e32 v120, 0xffffff76, v113
	v_max_i32_e32 v121, 0xffffff75, v113
	v_max_i32_e32 v122, 0xffffff70, v113
	v_max_i32_e32 v123, 0xffffff6f, v113
	v_max_i32_e32 v124, 0xffffff6e, v113
	v_max_i32_e32 v125, 0xffffff6d, v113
	v_max_i32_e32 v126, 0xffffff68, v113
	v_max_i32_e32 v127, 0xffffff67, v113
	v_max_i32_e32 v128, 0xffffff66, v113
	v_max_i32_e32 v130, 0xffffff65, v113
	v_lshl_add_u32 v136, v132, 2, s0
	v_max_i32_e32 v132, 0xffffff57, v113
	v_lshl_add_u32 v141, v140, 2, s0
	v_max_i32_e32 v140, 0xffffff4e, v113
	v_lshl_add_u32 v114, v114, 2, s0
	v_lshl_add_u32 v115, v115, 2, s0
	v_lshl_add_u32 v116, v116, 2, s0
	v_lshl_add_u32 v117, v117, 2, s0
	v_lshl_add_u32 v118, v118, 2, s0
	v_lshl_add_u32 v119, v119, 2, s0
	v_lshl_add_u32 v120, v120, 2, s0
	v_lshl_add_u32 v121, v121, 2, s0
	v_lshl_add_u32 v122, v122, 2, s0
	v_lshl_add_u32 v123, v123, 2, s0
	v_lshl_add_u32 v124, v124, 2, s0
	v_lshl_add_u32 v125, v125, 2, s0
	v_lshl_add_u32 v126, v126, 2, s0
	v_lshl_add_u32 v127, v127, 2, s0
	v_lshl_add_u32 v128, v128, 2, s0
	v_lshl_add_u32 v131, v130, 2, s0
	v_lshl_add_u32 v137, v132, 2, s0
	v_max_i32_e32 v132, 0xffffff56, v113
	v_lshl_add_u32 v142, v140, 2, s0
	v_max_i32_e32 v140, 0xffffff4d, v113
	ds_read_b32 v114, v114 offset:512
	ds_read_b32 v115, v115 offset:516
	ds_read_b32 v116, v116 offset:520
	ds_read_b32 v117, v117 offset:524
	ds_read_b32 v118, v118 offset:544
	ds_read_b32 v119, v119 offset:548
	ds_read_b32 v120, v120 offset:552
	ds_read_b32 v121, v121 offset:556
	ds_read_b32 v122, v122 offset:576
	ds_read_b32 v123, v123 offset:580
	ds_read_b32 v124, v124 offset:584
	ds_read_b32 v125, v125 offset:588
	ds_read_b32 v126, v126 offset:608
	ds_read_b32 v127, v127 offset:612
	ds_read_b32 v130, v128 offset:616
	ds_read_b32 v131, v131 offset:620
	v_max_i32_e32 v128, 0xffffff60, v113
	v_lshl_add_u32 v138, v132, 2, s0
	v_max_i32_e32 v132, 0xffffff55, v113
	v_lshl_add_u32 v143, v140, 2, s0
	v_max_i32_e32 v140, 0xffffff48, v113
	v_lshl_add_u32 v128, v128, 2, s0
	v_lshl_add_u32 v139, v132, 2, s0
	v_lshl_add_u32 v144, v140, 2, s0
	v_max_i32_e32 v140, 0xffffff47, v113
	ds_read_b32 v132, v128 offset:640
	ds_read_b32 v133, v133 offset:644
	ds_read_b32 v134, v134 offset:648
	ds_read_b32 v135, v135 offset:652
	ds_read_b32 v136, v136 offset:672
	ds_read_b32 v137, v137 offset:676
	ds_read_b32 v138, v138 offset:680
	ds_read_b32 v139, v139 offset:684
	v_max_i32_e32 v128, 0xffffff50, v113
	v_lshl_add_u32 v145, v140, 2, s0
	v_max_i32_e32 v140, 0xffffff46, v113
	v_lshl_add_u32 v128, v128, 2, s0
	v_lshl_add_u32 v146, v140, 2, s0
	v_max_i32_e32 v113, 0xffffff45, v113
	v_lshl_add_u32 v113, v113, 2, s0
	ds_read_b32 v140, v128 offset:704
	ds_read_b32 v141, v141 offset:708
	ds_read_b32 v142, v142 offset:712
	ds_read_b32 v143, v143 offset:716
	ds_read_b32 v144, v144 offset:736
	ds_read_b32 v145, v145 offset:740
	ds_read_b32 v146, v146 offset:744
	ds_read_b32 v147, v113 offset:748
	s_waitcnt lgkmcnt(14)
	v_pk_add_f32 v[78:79], v[78:79], v[130:131]
	v_pk_add_f32 v[76:77], v[76:77], v[126:127]
	v_pk_add_f32 v[74:75], v[74:75], v[124:125]
	v_pk_add_f32 v[72:73], v[72:73], v[122:123]
	v_pk_add_f32 v[70:71], v[70:71], v[120:121]
	v_pk_add_f32 v[68:69], v[68:69], v[118:119]
	v_pk_add_f32 v[66:67], v[66:67], v[116:117]
	v_pk_add_f32 v[64:65], v[64:65], v[114:115]
	s_waitcnt lgkmcnt(0)
	v_pk_add_f32 v[94:95], v[94:95], v[146:147]
	v_pk_add_f32 v[92:93], v[92:93], v[144:145]
	v_pk_add_f32 v[90:91], v[90:91], v[142:143]
	v_pk_add_f32 v[88:89], v[88:89], v[140:141]
	v_pk_add_f32 v[86:87], v[86:87], v[138:139]
	v_pk_add_f32 v[84:85], v[84:85], v[136:137]
	v_pk_add_f32 v[82:83], v[82:83], v[134:135]
	v_pk_add_f32 v[80:81], v[80:81], v[132:133]

; template <bool DIFF> ...
;     ...
;             const LAS unsigned char* kb_ = lds + buf * BUFB; const LAS unsigned char* vb_ = kb_ + KTILEB;
;             f32x16 pr[2];
;             const LAS unsigned char* vbase = vb_ + (4 * hi + ((lane & 15) >> 2)) * VROWB + (sdv + ((lane >> 4) & 1) * 16 + (lane & 3) * 4) * 2;
;     ...
;             bf16x8 vfa[NDB], vfb[NDB];
;             {
;                 bf16x8 kf[2][NS];
; #pragma unroll
;                 for (int kb = 0; kb < 2; ++kb)
; #pragma unroll
;                     for (int st = 0; st < NS; ++st) kf[kb][st] = *(const LAS bf16x8*)(kb_ + (kb * 32 + l32) * KROWB + (s * DQK + st * 16 + hi * 8) * 2);
;                 VLOAD(vfa, 0);
;                 __builtin_amdgcn_sched_barrier(0);
;                 __builtin_amdgcn_s_setprio(1);
; #pragma unroll
;                 for (int st = 0; st < NS; ++st) {
;                     pr[0] = __builtin_amdgcn_mfma_f32_32x32x16_bf16(kf[0][st], qf[st], st == 0 ? negm : pr[0], 0, 0, 0);
;                     pr[1] = __builtin_amdgcn_mfma_f32_32x32x16_bf16(kf[1][st], qf[st], st == 0 ? negm : pr[1], 0, 0, 0); }
;                 __builtin_amdgcn_s_setprio(0);
;             }
;             const int tp0 = (t == 0) ? -16 : (t - 1) * 64;
;             if (DIFF) {
;                 if (tp0 + 63 - qpos_w > -128) {
; #pragma unroll
;                     for (int kb = 0; kb < 2; ++kb)
; #pragma unroll
;                         for (int r = 0; r < 16; ++r) { const int kvi = kb * 32 + 8 * (r >> 2) + 4 * hi + (r & 3); int idx = tp0 + kvi - qpos + 128; idx = idx < 0 ? 0 : idx; pr[kb][r] += lut[idx]; }
;                 }
;             }
;             const int nval = (t == 0) ? 16 : (t == NT - 1 ? lastv : 64);
;             if (nval < 64) {
; #pragma unroll
;                 for (int kb = 0; kb < 2; ++kb)
; #pragma unroll
;                     for (int r = 0; r < 16; ++r) { const int kvi = kb * 32 + 8 * (r >> 2) + 4 * hi + (r & 3); if (kvi >= nval) pr[kb][r] = -INFINITY; }
;             }
;             float mx;
;             { float a0 = fmaxf(fmaxf(pr[0][0], pr[0][1]), pr[0][2]), a1 = fmaxf(fmaxf(pr[1][0], pr[1][1]), pr[1][2]);
; #pragma unroll
;               for (int r = 3; r < 15; r += 2) { a0 = fmaxf(fmaxf(a0, pr[0][r]), pr[0][r + 1]); a1 = fmaxf(fmaxf(a1, pr[1][r]), pr[1][r + 1]); }
;               mx = fmaxf(fmaxf(a0, a1), fmaxf(pr[0][15], pr[1][15])); }
.LBB0_697:
	s_and_b32 s40, s38, 1
	s_cmp_ge_u32 s38, s35
	s_cbranch_scc1 .LBB0_695
	s_mul_i32 s41, s40, 0xb400
	s_add_i32 s41, s41, 0
	v_add3_u32 v65, s41, v175, v174
	ds_read_b128 v[48:51], v65
	ds_read_b128 v[52:55], v65 offset:32
	ds_read_b128 v[56:59], v65 offset:64
	ds_read_b128 v[60:63], v65 offset:96
	ds_read_b128 v[186:189], v65 offset:128
	ds_read_b128 v[190:193], v65 offset:160
	ds_read_b128 v[202:205], v65 offset:12800
	ds_read_b128 v[206:209], v65 offset:12832
	ds_read_b128 v[210:213], v65 offset:12864
	ds_read_b128 v[214:217], v65 offset:12896
	ds_read_b128 v[218:221], v65 offset:12928
	ds_read_b128 v[222:225], v65 offset:12960
	v_add_u32_e32 v64, s41, v173
	v_add_u32_e32 v185, v64, v172
	ds_read_b64_tr_b16 v[142:143], v185 offset:25600
	ds_read_b64_tr_b16 v[144:145], v185 offset:28160
	ds_read_b64_tr_b16 v[148:149], v185 offset:28224
	ds_read_b64_tr_b16 v[146:147], v185 offset:25664
	s_setprio 1
	s_waitcnt lgkmcnt(14)
	v_mfma_f32_32x32x16_bf16 v[80:95], v[48:51], v[116:119], v[32:47]
	s_waitcnt lgkmcnt(9)
	v_mfma_f32_32x32x16_bf16 v[64:79], v[202:205], v[116:119], v[32:47]
	v_add_u32_e32 v48, s39, v184
	v_add_u32_e32 v50, s39, v183
	v_mad_i64_i32 v[48:49], s[40:41], v48, s2, v[156:157]
	v_mad_i64_i32 v[50:51], s[40:41], v50, s2, v[158:159]
	v_mfma_f32_32x32x16_bf16 v[80:95], v[52:55], v[112:115], v[80:95]
	global_load_dwordx4 v[124:127], v[48:49], off
	global_load_dwordx4 v[120:123], v[50:51], off
	s_waitcnt lgkmcnt(8)
	v_mfma_f32_32x32x16_bf16 v[64:79], v[206:209], v[112:115], v[64:79]
	v_add_u32_e32 v50, s39, v177
	v_add_u32_e32 v48, s39, v182
	v_ashrrev_i32_e32 v51, 31, v50
	v_mfma_f32_32x32x16_bf16 v[80:95], v[56:59], v[108:111], v[80:95]
	v_mad_i64_i32 v[48:49], s[40:41], v48, s2, v[160:161]
	v_lshlrev_b64 v[50:51], 10, v[50:51]
	v_lshl_add_u64 v[50:51], v[154:155], 0, v[50:51]
	s_waitcnt lgkmcnt(7)
	v_mfma_f32_32x32x16_bf16 v[64:79], v[210:213], v[108:111], v[64:79]
	global_load_dwordx4 v[134:137], v[48:49], off
	global_load_dwordx4 v[130:133], v[50:51], off
	v_mfma_f32_32x32x16_bf16 v[80:95], v[60:63], v[104:107], v[80:95]
	v_add_u32_e32 v48, s39, v176
	v_ashrrev_i32_e32 v49, 31, v48
	v_lshlrev_b64 v[48:49], 10, v[48:49]
	v_lshl_add_u64 v[48:49], v[154:155], 0, v[48:49]
	s_waitcnt lgkmcnt(6)
	v_mfma_f32_32x32x16_bf16 v[64:79], v[214:217], v[104:107], v[64:79]
	global_load_dwordx4 v[138:141], v[48:49], off
	s_and_b32 s40, s38, 1
	v_mfma_f32_32x32x16_bf16 v[80:95], v[186:189], v[100:103], v[80:95]
	s_waitcnt lgkmcnt(5)
	v_mfma_f32_32x32x16_bf16 v[64:79], v[218:221], v[100:103], v[64:79]
	v_mfma_f32_32x32x16_bf16 v[80:95], v[190:193], v[96:99], v[80:95]
	s_waitcnt lgkmcnt(4)
	v_mfma_f32_32x32x16_bf16 v[64:79], v[222:225], v[96:99], v[64:79]
	s_setprio 0
	ds_read_b64_tr_b16 v[202:203], v185 offset:30720
	ds_read_b64_tr_b16 v[204:205], v185 offset:33280
	ds_read_b64_tr_b16 v[206:207], v185 offset:30784
	ds_read_b64_tr_b16 v[208:209], v185 offset:33344
	s_nop 4
	v_max3_f32 v48, v80, v81, v82
	s_nop 0
	v_max3_f32 v49, v64, v65, v66
	v_max3_f32 v48, v48, v83, v84
	v_max3_f32 v49, v49, v67, v68
	v_max3_f32 v48, v48, v85, v86
	v_max3_f32 v49, v49, v69, v70
	v_max3_f32 v48, v48, v87, v88
	v_max3_f32 v49, v49, v71, v72
	v_max3_f32 v48, v48, v89, v90
	v_max3_f32 v49, v49, v73, v74
	v_max3_f32 v48, v48, v91, v92
	v_max3_f32 v49, v49, v75, v76
	v_max_f32_e32 v50, v79, v79
	v_max_f32_e32 v51, v95, v95
	v_max3_f32 v48, v48, v93, v94
	v_max3_f32 v49, v49, v77, v78
	v_max_f32_e32 v50, v51, v50
	v_max3_f32 v48, v48, v49, v50
	v_cmp_lt_f32_e32 vcc, s33, v48
	s_cbranch_vccz .LBB0_700
	ds_bpermute_b32 v49, v163, v48
	s_waitcnt lgkmcnt(0)
	v_max_f32_e32 v49, v49, v49
	v_max_f32_e32 v48, v48, v49
	v_max_f32_e32 v32, v48, v48
	v_max_f32_e32 v33, 0, v32
	v_exp_f32_e64 v34, -v33
	v_add_f32_e32 v152, v152, v33
	v_xor_b32_e32 v32, 0x80000000, v152
	v_sub_f32_e32 v80, v80, v33
	v_sub_f32_e32 v81, v81, v33
	v_sub_f32_e32 v82, v82, v33
	v_sub_f32_e32 v95, v95, v33
	v_sub_f32_e32 v83, v83, v33
	v_sub_f32_e32 v84, v84, v33
	v_sub_f32_e32 v85, v85, v33
	v_sub_f32_e32 v86, v86, v33
	v_sub_f32_e32 v87, v87, v33
	v_sub_f32_e32 v88, v88, v33
	v_sub_f32_e32 v89, v89, v33
	v_sub_f32_e32 v90, v90, v33
	v_sub_f32_e32 v91, v91, v33
	v_sub_f32_e32 v92, v92, v33
	v_sub_f32_e32 v93, v93, v33
	v_sub_f32_e32 v94, v94, v33
	v_sub_f32_e32 v64, v64, v33
	v_sub_f32_e32 v65, v65, v33
	v_sub_f32_e32 v66, v66, v33
	v_sub_f32_e32 v67, v67, v33
	v_sub_f32_e32 v68, v68, v33
	v_sub_f32_e32 v69, v69, v33
	v_sub_f32_e32 v70, v70, v33
	v_sub_f32_e32 v71, v71, v33
	v_sub_f32_e32 v72, v72, v33
	v_sub_f32_e32 v73, v73, v33
	v_sub_f32_e32 v74, v74, v33
	v_sub_f32_e32 v75, v75, v33
	v_sub_f32_e32 v76, v76, v33
	v_sub_f32_e32 v77, v77, v33
	v_sub_f32_e32 v78, v78, v33
	v_sub_f32_e32 v79, v79, v33
	v_pk_mul_f32 v[30:31], v[30:31], v[34:35] op_sel_hi:[1,0]
	v_pk_mul_f32 v[28:29], v[28:29], v[34:35] op_sel_hi:[1,0]
	v_pk_mul_f32 v[26:27], v[26:27], v[34:35] op_sel_hi:[1,0]
	v_pk_mul_f32 v[24:25], v[24:25], v[34:35] op_sel_hi:[1,0]
	v_pk_mul_f32 v[22:23], v[22:23], v[34:35] op_sel_hi:[1,0]
	v_pk_mul_f32 v[20:21], v[20:21], v[34:35] op_sel_hi:[1,0]
	v_pk_mul_f32 v[18:19], v[18:19], v[34:35] op_sel_hi:[1,0]
	v_pk_mul_f32 v[16:17], v[16:17], v[34:35] op_sel_hi:[1,0]
	v_pk_mul_f32 v[14:15], v[14:15], v[34:35] op_sel_hi:[1,0]
	v_pk_mul_f32 v[12:13], v[12:13], v[34:35] op_sel_hi:[1,0]
	v_pk_mul_f32 v[10:11], v[10:11], v[34:35] op_sel_hi:[1,0]
	v_pk_mul_f32 v[8:9], v[8:9], v[34:35] op_sel_hi:[1,0]
	v_pk_mul_f32 v[6:7], v[6:7], v[34:35] op_sel_hi:[1,0]
	v_pk_mul_f32 v[4:5], v[4:5], v[34:35] op_sel_hi:[1,0]
	v_pk_mul_f32 v[2:3], v[2:3], v[34:35] op_sel_hi:[1,0]
	v_pk_mul_f32 v[0:1], v[0:1], v[34:35] op_sel_hi:[1,0]
	v_mul_f32_e32 v153, v153, v34
	v_mov_b32_e32 v33, v32
	v_mov_b32_e32 v34, v32
	v_mov_b32_e32 v35, v32
	v_mov_b32_e32 v36, v32
	v_mov_b32_e32 v37, v32
	v_mov_b32_e32 v38, v32
	v_mov_b32_e32 v39, v32
	v_mov_b32_e32 v40, v32
	v_mov_b32_e32 v41, v32
	v_mov_b32_e32 v42, v32
	v_mov_b32_e32 v43, v32
	v_mov_b32_e32 v44, v32
	v_mov_b32_e32 v45, v32
	v_mov_b32_e32 v46, v32
	v_mov_b32_e32 v47, v32
	s_branch .LBB0_701
; template <bool DIFF> ...
;     ...
;             f32x2 ps2 = (f32x2){0.f, 0.f};
; #pragma unroll
;             for (int kb = 0; kb < 2; ++kb)
; #pragma unroll
;                 for (int r = 0; r < 16; r += 2) { const float e0 = __builtin_amdgcn_exp2f(pr[kb][r]), e1 = __builtin_amdgcn_exp2f(pr[kb][r + 1]); pr[kb][r] = e0; pr[kb][r + 1] = e1; ps2 += (f32x2){e0, e1}; }
;             lsum += ps2[0] + ps2[1];
;             __builtin_amdgcn_sched_barrier(0);
;             VLOAD(vfb, 1); __builtin_amdgcn_sched_barrier(0); PVMMA(vfa, 0); __builtin_amdgcn_sched_barrier(0);
;             VLOAD(vfa, 2); __builtin_amdgcn_sched_barrier(0); PVMMA(vfb, 1); __builtin_amdgcn_sched_barrier(0);
;             VLOAD(vfb, 3); __builtin_amdgcn_sched_barrier(0); PVMMA(vfa, 2); __builtin_amdgcn_sched_barrier(0);
;             PVMMA(vfb, 3);
;     ...
;         }
;         if (t + 1 < NT) ATT_LSTORE(buf ^ 1);
.LBB0_700:
.LBB0_701:
	v_exp_f32_e32 v210, v80
	v_exp_f32_e32 v211, v81
	v_exp_f32_e32 v212, v82
	v_exp_f32_e32 v213, v83
	v_pk_add_f32 v[54:55], v[210:211], 0 op_sel_hi:[1,0]
	v_exp_f32_e32 v214, v84
	v_exp_f32_e32 v215, v85
	v_pk_add_f32 v[54:55], v[212:213], v[54:55]
	v_exp_f32_e32 v80, v86
	v_exp_f32_e32 v81, v87
	v_pk_add_f32 v[54:55], v[214:215], v[54:55]
	v_cvt_pk_bf16_f32 v216, v210, v211
	v_cvt_pk_bf16_f32 v217, v212, v213
	v_cvt_pk_bf16_f32 v218, v214, v215
	v_cvt_pk_bf16_f32 v219, v80, v81
	s_setprio 1
	v_pk_add_f32 v[54:55], v[80:81], v[54:55]
	s_waitcnt lgkmcnt(4)
	v_mfma_f32_32x32x16_bf16 v[16:31], v[142:145], v[216:219], v[16:31]
	v_exp_f32_e32 v82, v88
	v_exp_f32_e32 v83, v89
	v_exp_f32_e32 v84, v90
	v_exp_f32_e32 v85, v91
	v_pk_add_f32 v[54:55], v[82:83], v[54:55]
	v_mfma_f32_32x32x16_bf16 v[0:15], v[146:149], v[216:219], v[0:15]
	v_exp_f32_e32 v86, v92
	v_exp_f32_e32 v87, v93
	v_exp_f32_e32 v88, v94
	v_exp_f32_e32 v89, v95
	v_pk_add_f32 v[54:55], v[84:85], v[54:55]
	v_pk_add_f32 v[54:55], v[86:87], v[54:55]
	ds_read_b64_tr_b16 v[220:221], v185 offset:35840
	ds_read_b64_tr_b16 v[222:223], v185 offset:38400
	ds_read_b64_tr_b16 v[226:227], v185 offset:38464
	ds_read_b64_tr_b16 v[224:225], v185 offset:35904
	v_cvt_pk_bf16_f32 v228, v82, v83
	v_cvt_pk_bf16_f32 v229, v84, v85
	v_cvt_pk_bf16_f32 v230, v86, v87
	v_cvt_pk_bf16_f32 v231, v88, v89
	v_pk_add_f32 v[54:55], v[88:89], v[54:55]
	s_waitcnt lgkmcnt(6)
	v_mfma_f32_32x32x16_bf16 v[16:31], v[202:205], v[228:231], v[16:31]
	v_exp_f32_e32 v90, v64
	v_exp_f32_e32 v91, v65
	v_exp_f32_e32 v92, v66
	v_exp_f32_e32 v93, v67
	v_pk_add_f32 v[54:55], v[90:91], v[54:55]
	s_waitcnt lgkmcnt(4)
	v_mfma_f32_32x32x16_bf16 v[0:15], v[206:209], v[228:231], v[0:15]
	v_exp_f32_e32 v94, v68
	v_exp_f32_e32 v95, v69
	v_exp_f32_e32 v198, v70
	v_exp_f32_e32 v199, v71
	v_pk_add_f32 v[54:55], v[92:93], v[54:55]
	v_pk_add_f32 v[54:55], v[94:95], v[54:55]
	ds_read_b64_tr_b16 v[202:203], v185 offset:40960
	ds_read_b64_tr_b16 v[204:205], v185 offset:43520
	ds_read_b64_tr_b16 v[208:209], v185 offset:43584
	ds_read_b64_tr_b16 v[206:207], v185 offset:41024
	v_cvt_pk_bf16_f32 v228, v90, v91
	v_cvt_pk_bf16_f32 v229, v92, v93
	v_cvt_pk_bf16_f32 v230, v94, v95
	v_cvt_pk_bf16_f32 v231, v198, v199
	v_pk_add_f32 v[54:55], v[198:199], v[54:55]
	s_waitcnt lgkmcnt(6)
	v_mfma_f32_32x32x16_bf16 v[16:31], v[220:223], v[228:231], v[16:31]
	v_exp_f32_e32 v72, v72
	v_exp_f32_e32 v73, v73
	v_exp_f32_e32 v74, v74
	v_exp_f32_e32 v75, v75
	v_pk_add_f32 v[54:55], v[72:73], v[54:55]
	s_waitcnt lgkmcnt(4)
	v_mfma_f32_32x32x16_bf16 v[0:15], v[224:227], v[228:231], v[0:15]
	v_exp_f32_e32 v76, v76
	v_exp_f32_e32 v77, v77
	v_exp_f32_e32 v78, v78
	v_exp_f32_e32 v79, v79
	v_pk_add_f32 v[54:55], v[74:75], v[54:55]
	v_pk_add_f32 v[54:55], v[76:77], v[54:55]
	v_cvt_pk_bf16_f32 v216, v72, v73
	v_cvt_pk_bf16_f32 v217, v74, v75
	v_cvt_pk_bf16_f32 v218, v76, v77
	v_cvt_pk_bf16_f32 v219, v78, v79
	v_pk_add_f32 v[54:55], v[78:79], v[54:55]
	s_nop 0
	v_add_f32_e32 v52, v54, v55
	s_waitcnt lgkmcnt(2)
	v_mfma_f32_32x32x16_bf16 v[16:31], v[202:205], v[216:219], v[16:31]
	v_add_f32_e32 v153, v153, v52
	s_xor_b32 s41, s40, 1
	s_mul_i32 s41, s41, 0xb400
	v_add3_u32 v64, s41, v164, v165
	s_waitcnt vmcnt(4)
	ds_write_b128 v64, v[124:127]
	v_add3_u32 v64, s41, v166, v167
	s_waitcnt vmcnt(3)
	ds_write_b128 v64, v[120:123]
	s_waitcnt lgkmcnt(2)
	v_mfma_f32_32x32x16_bf16 v[0:15], v[206:209], v[216:219], v[0:15]
	v_add3_u32 v64, s41, v168, v169
	s_waitcnt vmcnt(2)
	ds_write_b128 v64, v[134:137]
	v_add_u32_e32 v64, s41, v128
	v_add_u32_e32 v65, v64, v170
	v_add_u32_e32 v64, v64, v171
	s_waitcnt vmcnt(1)
	ds_write_b128 v65, v[130:133] offset:25600
	s_waitcnt vmcnt(0)
	ds_write_b128 v64, v[138:141] offset:25600
	s_setprio 0
	s_branch .Ltail2_m1

; template <bool DIFF> ...
;     ...
;             const LAS unsigned char* kb_ = lds + buf * BUFB; const LAS unsigned char* vb_ = kb_ + KTILEB;
;             f32x16 pr[2];
;             const LAS unsigned char* vbase = vb_ + (4 * hi + ((lane & 15) >> 2)) * VROWB + (sdv + ((lane >> 4) & 1) * 16 + (lane & 3) * 4) * 2;
;     ...
;             bf16x8 vfa[NDB], vfb[NDB];
;             {
;                 bf16x8 kf[2][NS];
; #pragma unroll
;                 for (int kb = 0; kb < 2; ++kb)
; #pragma unroll
;                     for (int st = 0; st < NS; ++st) kf[kb][st] = *(const LAS bf16x8*)(kb_ + (kb * 32 + l32) * KROWB + (s * DQK + st * 16 + hi * 8) * 2);
;                 VLOAD(vfa, 0);
;                 __builtin_amdgcn_sched_barrier(0);
;                 __builtin_amdgcn_s_setprio(1);
; #pragma unroll
;                 for (int st = 0; st < NS; ++st) {
;                     pr[0] = __builtin_amdgcn_mfma_f32_32x32x16_bf16(kf[0][st], qf[st], st == 0 ? negm : pr[0], 0, 0, 0);
;                     pr[1] = __builtin_amdgcn_mfma_f32_32x32x16_bf16(kf[1][st], qf[st], st == 0 ? negm : pr[1], 0, 0, 0); }
;                 __builtin_amdgcn_s_setprio(0);
;             }
;             const int tp0 = (t == 0) ? -16 : (t - 1) * 64;
;             if (DIFF) {
;                 if (tp0 + 63 - qpos_w > -128) {
; #pragma unroll
;                     for (int kb = 0; kb < 2; ++kb)
; #pragma unroll
;                         for (int r = 0; r < 16; ++r) { const int kvi = kb * 32 + 8 * (r >> 2) + 4 * hi + (r & 3); int idx = tp0 + kvi - qpos + 128; idx = idx < 0 ? 0 : idx; pr[kb][r] += lut[idx]; }
;                 }
;             }
;             const int nval = (t == 0) ? 16 : (t == NT - 1 ? lastv : 64);
;             if (nval < 64) {
; #pragma unroll
;                 for (int kb = 0; kb < 2; ++kb)
; #pragma unroll
;                     for (int r = 0; r < 16; ++r) { const int kvi = kb * 32 + 8 * (r >> 2) + 4 * hi + (r & 3); if (kvi >= nval) pr[kb][r] = -INFINITY; }
;             }
;             float mx;
;             { float a0 = fmaxf(fmaxf(pr[0][0], pr[0][1]), pr[0][2]), a1 = fmaxf(fmaxf(pr[1][0], pr[1][1]), pr[1][2]);
; #pragma unroll
;               for (int r = 3; r < 15; r += 2) { a0 = fmaxf(fmaxf(a0, pr[0][r]), pr[0][r + 1]); a1 = fmaxf(fmaxf(a1, pr[1][r]), pr[1][r + 1]); }
;               mx = fmaxf(fmaxf(a0, a1), fmaxf(pr[0][15], pr[1][15])); }
.LBB0_709:
	s_and_b32 s1, s18, 1
	s_cmp_ge_u32 s18, s19
	s_cbranch_scc1 .LBB0_707
	s_mul_i32 s16, s1, 0xb400
	s_add_i32 s16, s16, 0
	v_add3_u32 v65, s16, v175, v174
	ds_read_b128 v[48:51], v65
	ds_read_b128 v[52:55], v65 offset:32
	ds_read_b128 v[56:59], v65 offset:64
	ds_read_b128 v[60:63], v65 offset:96
	ds_read_b128 v[186:189], v65 offset:128
	ds_read_b128 v[190:193], v65 offset:160
	ds_read_b128 v[202:205], v65 offset:12800
	ds_read_b128 v[206:209], v65 offset:12832
	ds_read_b128 v[210:213], v65 offset:12864
	ds_read_b128 v[214:217], v65 offset:12896
	ds_read_b128 v[218:221], v65 offset:12928
	ds_read_b128 v[222:225], v65 offset:12960
	v_add_u32_e32 v64, s16, v173
	v_add_u32_e32 v185, v64, v172
	ds_read_b64_tr_b16 v[142:143], v185 offset:25600
	ds_read_b64_tr_b16 v[144:145], v185 offset:28160
	ds_read_b64_tr_b16 v[148:149], v185 offset:28224
	ds_read_b64_tr_b16 v[146:147], v185 offset:25664
	s_setprio 1
	s_waitcnt lgkmcnt(14)
	v_mfma_f32_32x32x16_bf16 v[80:95], v[48:51], v[116:119], v[32:47]
	s_waitcnt lgkmcnt(9)
	v_mfma_f32_32x32x16_bf16 v[64:79], v[202:205], v[116:119], v[32:47]
	v_add_u32_e32 v48, s20, v184
	v_add_u32_e32 v50, s20, v183
	v_mad_i64_i32 v[48:49], s[22:23], v48, s2, v[156:157]
	v_mad_i64_i32 v[50:51], s[22:23], v50, s2, v[158:159]
	v_mfma_f32_32x32x16_bf16 v[80:95], v[52:55], v[112:115], v[80:95]
	global_load_dwordx4 v[124:127], v[48:49], off
	global_load_dwordx4 v[120:123], v[50:51], off
	s_waitcnt lgkmcnt(8)
	v_mfma_f32_32x32x16_bf16 v[64:79], v[206:209], v[112:115], v[64:79]
	v_add_u32_e32 v50, s20, v177
	v_add_u32_e32 v48, s20, v182
	v_ashrrev_i32_e32 v51, 31, v50
	v_mfma_f32_32x32x16_bf16 v[80:95], v[56:59], v[108:111], v[80:95]
	v_mad_i64_i32 v[48:49], s[22:23], v48, s2, v[160:161]
	v_lshlrev_b64 v[50:51], 10, v[50:51]
	v_lshl_add_u64 v[50:51], v[154:155], 0, v[50:51]
	s_waitcnt lgkmcnt(7)
	v_mfma_f32_32x32x16_bf16 v[64:79], v[210:213], v[108:111], v[64:79]
	global_load_dwordx4 v[134:137], v[48:49], off
	global_load_dwordx4 v[130:133], v[50:51], off
	v_mfma_f32_32x32x16_bf16 v[80:95], v[60:63], v[104:107], v[80:95]
	v_add_u32_e32 v48, s20, v176
	v_ashrrev_i32_e32 v49, 31, v48
	v_lshlrev_b64 v[48:49], 10, v[48:49]
	v_lshl_add_u64 v[48:49], v[154:155], 0, v[48:49]
	s_waitcnt lgkmcnt(6)
	v_mfma_f32_32x32x16_bf16 v[64:79], v[214:217], v[104:107], v[64:79]
	global_load_dwordx4 v[138:141], v[48:49], off
	v_mfma_f32_32x32x16_bf16 v[80:95], v[186:189], v[100:103], v[80:95]
	s_waitcnt lgkmcnt(5)
	v_mfma_f32_32x32x16_bf16 v[64:79], v[218:221], v[100:103], v[64:79]
	v_mfma_f32_32x32x16_bf16 v[80:95], v[190:193], v[96:99], v[80:95]
	s_waitcnt lgkmcnt(4)
	v_mfma_f32_32x32x16_bf16 v[64:79], v[222:225], v[96:99], v[64:79]
	s_setprio 0
	ds_read_b64_tr_b16 v[202:203], v185 offset:30720
	ds_read_b64_tr_b16 v[204:205], v185 offset:33280
	ds_read_b64_tr_b16 v[206:207], v185 offset:30784
	ds_read_b64_tr_b16 v[208:209], v185 offset:33344
	s_nop 4
	v_max3_f32 v48, v80, v81, v82
	s_nop 0
	v_max3_f32 v49, v64, v65, v66
	v_max3_f32 v48, v48, v83, v84
	v_max3_f32 v49, v49, v67, v68
	v_max3_f32 v48, v48, v85, v86
	v_max3_f32 v49, v49, v69, v70
	v_max3_f32 v48, v48, v87, v88
	v_max3_f32 v49, v49, v71, v72
	v_max3_f32 v48, v48, v89, v90
	v_max3_f32 v49, v49, v73, v74
	v_max3_f32 v48, v48, v91, v92
	v_max3_f32 v49, v49, v75, v76
	v_max_f32_e32 v50, v79, v79
	v_max_f32_e32 v51, v95, v95
	v_max3_f32 v48, v48, v93, v94
	v_max3_f32 v49, v49, v77, v78
	v_max_f32_e32 v50, v51, v50
	v_max3_f32 v48, v48, v49, v50
	v_cmp_lt_f32_e32 vcc, s33, v48
	s_cbranch_vccz .LBB0_712
	ds_bpermute_b32 v49, v163, v48
	s_waitcnt lgkmcnt(0)
	v_max_f32_e32 v49, v49, v49
	v_max_f32_e32 v48, v48, v49
	v_max_f32_e32 v32, v48, v48
	v_max_f32_e32 v33, 0, v32
	v_exp_f32_e64 v34, -v33
	v_add_f32_e32 v152, v152, v33
	v_xor_b32_e32 v32, 0x80000000, v152
	v_sub_f32_e32 v80, v80, v33
	v_sub_f32_e32 v81, v81, v33
	v_sub_f32_e32 v82, v82, v33
	v_sub_f32_e32 v95, v95, v33
	v_sub_f32_e32 v83, v83, v33
	v_sub_f32_e32 v84, v84, v33
	v_sub_f32_e32 v85, v85, v33
	v_sub_f32_e32 v86, v86, v33
	v_sub_f32_e32 v87, v87, v33
	v_sub_f32_e32 v88, v88, v33
	v_sub_f32_e32 v89, v89, v33
	v_sub_f32_e32 v90, v90, v33
	v_sub_f32_e32 v91, v91, v33
	v_sub_f32_e32 v92, v92, v33
	v_sub_f32_e32 v93, v93, v33
	v_sub_f32_e32 v94, v94, v33
	v_sub_f32_e32 v64, v64, v33
	v_sub_f32_e32 v65, v65, v33
	v_sub_f32_e32 v66, v66, v33
	v_sub_f32_e32 v67, v67, v33
	v_sub_f32_e32 v68, v68, v33
	v_sub_f32_e32 v69, v69, v33
	v_sub_f32_e32 v70, v70, v33
	v_sub_f32_e32 v71, v71, v33
	v_sub_f32_e32 v72, v72, v33
	v_sub_f32_e32 v73, v73, v33
	v_sub_f32_e32 v74, v74, v33
	v_sub_f32_e32 v75, v75, v33
	v_sub_f32_e32 v76, v76, v33
	v_sub_f32_e32 v77, v77, v33
	v_sub_f32_e32 v78, v78, v33
	v_sub_f32_e32 v79, v79, v33
	v_pk_mul_f32 v[30:31], v[30:31], v[34:35] op_sel_hi:[1,0]
	v_pk_mul_f32 v[28:29], v[28:29], v[34:35] op_sel_hi:[1,0]
	v_pk_mul_f32 v[26:27], v[26:27], v[34:35] op_sel_hi:[1,0]
	v_pk_mul_f32 v[24:25], v[24:25], v[34:35] op_sel_hi:[1,0]
	v_pk_mul_f32 v[22:23], v[22:23], v[34:35] op_sel_hi:[1,0]
	v_pk_mul_f32 v[20:21], v[20:21], v[34:35] op_sel_hi:[1,0]
	v_pk_mul_f32 v[18:19], v[18:19], v[34:35] op_sel_hi:[1,0]
	v_pk_mul_f32 v[16:17], v[16:17], v[34:35] op_sel_hi:[1,0]
	v_pk_mul_f32 v[14:15], v[14:15], v[34:35] op_sel_hi:[1,0]
	v_pk_mul_f32 v[12:13], v[12:13], v[34:35] op_sel_hi:[1,0]
	v_pk_mul_f32 v[10:11], v[10:11], v[34:35] op_sel_hi:[1,0]
	v_pk_mul_f32 v[8:9], v[8:9], v[34:35] op_sel_hi:[1,0]
	v_pk_mul_f32 v[6:7], v[6:7], v[34:35] op_sel_hi:[1,0]
	v_pk_mul_f32 v[4:5], v[4:5], v[34:35] op_sel_hi:[1,0]
	v_pk_mul_f32 v[2:3], v[2:3], v[34:35] op_sel_hi:[1,0]
	v_pk_mul_f32 v[0:1], v[0:1], v[34:35] op_sel_hi:[1,0]
	v_mul_f32_e32 v153, v153, v34
	v_mov_b32_e32 v33, v32
	v_mov_b32_e32 v34, v32
	v_mov_b32_e32 v35, v32
	v_mov_b32_e32 v36, v32
	v_mov_b32_e32 v37, v32
	v_mov_b32_e32 v38, v32
	v_mov_b32_e32 v39, v32
	v_mov_b32_e32 v40, v32
	v_mov_b32_e32 v41, v32
	v_mov_b32_e32 v42, v32
	v_mov_b32_e32 v43, v32
	v_mov_b32_e32 v44, v32
	v_mov_b32_e32 v45, v32
	v_mov_b32_e32 v46, v32
	v_mov_b32_e32 v47, v32
	s_branch .LBB0_713
; template <bool DIFF> ...
;     ...
;             f32x2 ps2 = (f32x2){0.f, 0.f};
; #pragma unroll
;             for (int kb = 0; kb < 2; ++kb)
; #pragma unroll
;                 for (int r = 0; r < 16; r += 2) { const float e0 = __builtin_amdgcn_exp2f(pr[kb][r]), e1 = __builtin_amdgcn_exp2f(pr[kb][r + 1]); pr[kb][r] = e0; pr[kb][r + 1] = e1; ps2 += (f32x2){e0, e1}; }
;             lsum += ps2[0] + ps2[1];
;             __builtin_amdgcn_sched_barrier(0);
;             VLOAD(vfb, 1); __builtin_amdgcn_sched_barrier(0); PVMMA(vfa, 0); __builtin_amdgcn_sched_barrier(0);
;             VLOAD(vfa, 2); __builtin_amdgcn_sched_barrier(0); PVMMA(vfb, 1); __builtin_amdgcn_sched_barrier(0);
;             VLOAD(vfb, 3); __builtin_amdgcn_sched_barrier(0); PVMMA(vfa, 2); __builtin_amdgcn_sched_barrier(0);
;             PVMMA(vfb, 3);
;     ...
;         }
;         if (t + 1 < NT) ATT_LSTORE(buf ^ 1);
.LBB0_712:
.LBB0_713:
	v_exp_f32_e32 v210, v80
	v_exp_f32_e32 v211, v81
	v_exp_f32_e32 v212, v82
	v_exp_f32_e32 v213, v83
	v_pk_add_f32 v[54:55], v[210:211], 0 op_sel_hi:[1,0]
	v_exp_f32_e32 v214, v84
	v_exp_f32_e32 v215, v85
	v_pk_add_f32 v[54:55], v[212:213], v[54:55]
	v_exp_f32_e32 v80, v86
	v_exp_f32_e32 v81, v87
	v_pk_add_f32 v[54:55], v[214:215], v[54:55]
	v_cvt_pk_bf16_f32 v216, v210, v211
	v_cvt_pk_bf16_f32 v217, v212, v213
	v_cvt_pk_bf16_f32 v218, v214, v215
	v_cvt_pk_bf16_f32 v219, v80, v81
	s_setprio 1
	v_pk_add_f32 v[54:55], v[80:81], v[54:55]
	s_waitcnt lgkmcnt(4)
	v_mfma_f32_32x32x16_bf16 v[16:31], v[142:145], v[216:219], v[16:31]
	v_exp_f32_e32 v82, v88
	v_exp_f32_e32 v83, v89
	v_exp_f32_e32 v84, v90
	v_exp_f32_e32 v85, v91
	v_pk_add_f32 v[54:55], v[82:83], v[54:55]
	v_mfma_f32_32x32x16_bf16 v[0:15], v[146:149], v[216:219], v[0:15]
	v_exp_f32_e32 v86, v92
	v_exp_f32_e32 v87, v93
	v_exp_f32_e32 v88, v94
	v_exp_f32_e32 v89, v95
	v_pk_add_f32 v[54:55], v[84:85], v[54:55]
	v_pk_add_f32 v[54:55], v[86:87], v[54:55]
	ds_read_b64_tr_b16 v[220:221], v185 offset:35840
	ds_read_b64_tr_b16 v[222:223], v185 offset:38400
	ds_read_b64_tr_b16 v[226:227], v185 offset:38464
	ds_read_b64_tr_b16 v[224:225], v185 offset:35904
	v_cvt_pk_bf16_f32 v228, v82, v83
	v_cvt_pk_bf16_f32 v229, v84, v85
	v_cvt_pk_bf16_f32 v230, v86, v87
	v_cvt_pk_bf16_f32 v231, v88, v89
	v_pk_add_f32 v[54:55], v[88:89], v[54:55]
	s_waitcnt lgkmcnt(6)
	v_mfma_f32_32x32x16_bf16 v[16:31], v[202:205], v[228:231], v[16:31]
	v_exp_f32_e32 v90, v64
	v_exp_f32_e32 v91, v65
	v_exp_f32_e32 v92, v66
	v_exp_f32_e32 v93, v67
	v_pk_add_f32 v[54:55], v[90:91], v[54:55]
	s_waitcnt lgkmcnt(4)
	v_mfma_f32_32x32x16_bf16 v[0:15], v[206:209], v[228:231], v[0:15]
	v_exp_f32_e32 v94, v68
	v_exp_f32_e32 v95, v69
	v_exp_f32_e32 v198, v70
	v_exp_f32_e32 v199, v71
	v_pk_add_f32 v[54:55], v[92:93], v[54:55]
	v_pk_add_f32 v[54:55], v[94:95], v[54:55]
	ds_read_b64_tr_b16 v[202:203], v185 offset:40960
	ds_read_b64_tr_b16 v[204:205], v185 offset:43520
	ds_read_b64_tr_b16 v[208:209], v185 offset:43584
	ds_read_b64_tr_b16 v[206:207], v185 offset:41024
	v_cvt_pk_bf16_f32 v228, v90, v91
	v_cvt_pk_bf16_f32 v229, v92, v93
	v_cvt_pk_bf16_f32 v230, v94, v95
	v_cvt_pk_bf16_f32 v231, v198, v199
	v_pk_add_f32 v[54:55], v[198:199], v[54:55]
	s_waitcnt lgkmcnt(6)
	v_mfma_f32_32x32x16_bf16 v[16:31], v[220:223], v[228:231], v[16:31]
	v_exp_f32_e32 v72, v72
	v_exp_f32_e32 v73, v73
	v_exp_f32_e32 v74, v74
	v_exp_f32_e32 v75, v75
	v_pk_add_f32 v[54:55], v[72:73], v[54:55]
	s_waitcnt lgkmcnt(4)
	v_mfma_f32_32x32x16_bf16 v[0:15], v[224:227], v[228:231], v[0:15]
	v_exp_f32_e32 v76, v76
	v_exp_f32_e32 v77, v77
	v_exp_f32_e32 v78, v78
	v_exp_f32_e32 v79, v79
	v_pk_add_f32 v[54:55], v[74:75], v[54:55]
	v_pk_add_f32 v[54:55], v[76:77], v[54:55]
	v_cvt_pk_bf16_f32 v216, v72, v73
	v_cvt_pk_bf16_f32 v217, v74, v75
	v_cvt_pk_bf16_f32 v218, v76, v77
	v_cvt_pk_bf16_f32 v219, v78, v79
	v_pk_add_f32 v[54:55], v[78:79], v[54:55]
	s_nop 0
	v_add_f32_e32 v52, v54, v55
	s_waitcnt lgkmcnt(2)
	v_mfma_f32_32x32x16_bf16 v[16:31], v[202:205], v[216:219], v[16:31]
	v_add_f32_e32 v153, v153, v52
	s_xor_b32 s16, s1, 1
	s_mul_i32 s16, s16, 0xb400
	v_add3_u32 v64, s16, v164, v165
	s_waitcnt vmcnt(4)
	ds_write_b128 v64, v[124:127]
	v_add3_u32 v64, s16, v166, v167
	s_waitcnt vmcnt(3)
	ds_write_b128 v64, v[120:123]
	s_waitcnt lgkmcnt(2)
	v_mfma_f32_32x32x16_bf16 v[0:15], v[206:209], v[216:219], v[0:15]
	v_add3_u32 v64, s16, v168, v169
	s_waitcnt vmcnt(2)
	ds_write_b128 v64, v[134:137]
	v_add_u32_e32 v64, s16, v128
	v_add_u32_e32 v65, v64, v170
	v_add_u32_e32 v64, v64, v171
	s_waitcnt vmcnt(1)
	ds_write_b128 v65, v[130:133] offset:25600
	s_waitcnt vmcnt(0)
	ds_write_b128 v64, v[138:141] offset:25600
	s_setprio 0
	s_branch .Ltail2_m2
